# K-loop LDS-DMA loads use scalar base + 32-bit offset instead of a VALU 64-bit address add (4 of 5 GEMM loops)
# baseline (speedup 1.0000x reference)
; #define PG8_STAGE(bufoff, gbase, voff) do { _Pragma("unroll") for (int _i = 0; _i < 2; ++_i) \
;         __builtin_amdgcn_global_load_lds((const unsigned*)((const char*)(gbase) + (voff)[_i]), (LAS unsigned*)(lds + (bufoff) + ldsw + _i * 8192), 16, 0, 0); } while (0)
; #define PG8_LDA(dst, b, h) do { _Pragma("unroll") for (int m = 0; m < 4; ++m) _Pragma("unroll") for (int k = 0; k < 2; ++k) dst[m][k] = *(const LAS bf16x8*)(lds + PG8_SA(b, h) + aoff + m * 2048 + k * 1024); } while (0)
; #define PG8_LDB(dst, b, h) do { _Pragma("unroll") for (int n = 0; n < 2; ++n) _Pragma("unroll") for (int k = 0; k < 2; ++k) dst[n][k] = *(const LAS bf16x8*)(lds + PG8_SB(b, h) + boff + n * 2048 + k * 1024); } while (0)
; #define PG8_WAIT_V(n) asm volatile("s_waitcnt vmcnt(" #n ")" ::: "memory")
; #define PG8_WAIT_L(n) asm volatile("s_waitcnt lgkmcnt(" #n ")" ::: "memory")
; #define PG8_BAR __builtin_amdgcn_s_barrier()
; #define PG8_SCHED __builtin_amdgcn_sched_barrier(0)
; template <class Epi>
; __device__ __forceinline__ void gemm_phase(LAS unsigned char* lds, const Gemm g, const Order& S, const Epi& E) {
;     ...
;         const bool has_next = S.next(ui + 1, nxt);
;         const char* nA = has_next ? (const char*)(g.A + (size_t)nxt.pm * BM * g.lda + (size_t)nxt.z * g.za) : cA;
;         const char* nB = has_next ? (const char*)(g.Bt + (size_t)nxt.pn * BM * g.ldb + (size_t)nxt.z * g.zb) : cB;
;         for (int t = 0; t < nt; t += 2) {
;             const bool last = (t == nt - 2);
;             const char* a1 = cA + (size_t)(t + 1) * kstep;
;             const char* a2 = last ? nA : cA + (size_t)(t + 2) * kstep; const char* b2 = last ? nB : cB + (size_t)(t + 2) * kstep;
;             const char* a3 = a2 + kstep; const char* b3 = b2 + kstep;
;             PG8_LDB(B0, 0, 0); PG8_LDB(B1, 0, 1); PG8_SCHED; PG8_LDA(At, 0, 0); PG8_STAGE(PG8_SA(1, 1), a1 + hstepA, voffA);
;             PG8_WAIT_V(8); PG8_WAIT_L(0); PG8_BAR; PG8_MMA(0, 0, At, B0); PG8_MMA(0, 1, At, B1); PG8_BAR; PG8_SCHED;
;             PG8_LDA(At, 0, 1); PG8_STAGE(PG8_SB(0, 0), b2, voffB); PG8_STAGE(PG8_SB(0, 1), b2 + hstepB, voffB); PG8_STAGE(PG8_SA(0, 0), a2, voffA);
;             PG8_WAIT_V(8); PG8_WAIT_L(0); PG8_BAR; PG8_MMA(1, 0, At, B0); PG8_MMA(1, 1, At, B1); PG8_BAR; PG8_SCHED;
.LBB0_81:
	s_add_u32 s4, s40, 0xfffc0080
	s_addc_u32 s5, s41, -1
	s_add_i32 s6, 0, 0x10000
	s_cmp_eq_u32 vcc_lo, 12
	s_cselect_b32 s71, s34, s5
	s_cselect_b32 s70, s35, s4
	v_add_u32_e32 v142, s6, v145
	s_cselect_b32 s69, s45, s89
	s_cselect_b32 s68, s47, s88
	s_add_i32 s7, 0, 0x14000
	ds_read_b128 v[138:141], v142
	ds_read_b128 v[148:151], v142 offset:1024
	ds_read_b128 v[152:155], v142 offset:2048
	ds_read_b128 v[156:159], v142 offset:3072
	v_add_u32_e32 v142, s7, v145
	ds_read_b128 v[172:175], v142
	ds_read_b128 v[176:179], v142 offset:1024
	ds_read_b128 v[180:183], v142 offset:2048
	ds_read_b128 v[184:187], v142 offset:3072
	s_add_i32 m0, s24, 0xc000
	ds_read_b128 v[188:191], v147
	ds_read_b128 v[192:195], v147 offset:1024
	ds_read_b128 v[214:217], v147 offset:2048
	ds_read_b128 v[218:221], v147 offset:3072
	ds_read_b128 v[222:225], v147 offset:4096
	ds_read_b128 v[226:229], v147 offset:5120
	ds_read_b128 v[230:233], v147 offset:6144
	ds_read_b128 v[234:237], v147 offset:7168
	global_load_lds_dwordx4 v134, s[40:41]
	s_add_i32 m0, s24, 0xe000
	s_nop 0
	global_load_lds_dwordx4 v136, s[40:41]
	s_waitcnt vmcnt(8)
	s_waitcnt lgkmcnt(0)
	s_barrier
	s_setprio 1
	s_waitcnt lgkmcnt(0)
	v_mfma_f32_16x16x32_f16 v[124:127], v[138:141], v[188:191], v[124:127]
	v_mfma_f32_16x16x32_f16 v[120:123], v[152:155], v[188:191], v[120:123]
	v_mfma_f32_16x16x32_f16 v[108:111], v[138:141], v[214:217], v[108:111]
	v_mfma_f32_16x16x32_f16 v[104:107], v[152:155], v[214:217], v[104:107]
	v_mfma_f32_16x16x32_f16 v[92:95], v[138:141], v[222:225], v[92:95]
	v_mfma_f32_16x16x32_f16 v[88:91], v[152:155], v[222:225], v[88:91]
	v_mfma_f32_16x16x32_f16 v[76:79], v[138:141], v[230:233], v[76:79]
	v_mfma_f32_16x16x32_f16 v[72:75], v[152:155], v[230:233], v[72:75]
	v_mfma_f32_16x16x32_f16 v[124:127], v[148:151], v[192:195], v[124:127]
	v_mfma_f32_16x16x32_f16 v[120:123], v[156:159], v[192:195], v[120:123]
	v_mfma_f32_16x16x32_f16 v[108:111], v[148:151], v[218:221], v[108:111]
	v_mfma_f32_16x16x32_f16 v[104:107], v[156:159], v[218:221], v[104:107]
	v_mfma_f32_16x16x32_f16 v[92:95], v[148:151], v[226:229], v[92:95]
	v_mfma_f32_16x16x32_f16 v[88:91], v[156:159], v[226:229], v[88:91]
	v_mfma_f32_16x16x32_f16 v[76:79], v[148:151], v[234:237], v[76:79]
	v_mfma_f32_16x16x32_f16 v[72:75], v[156:159], v[234:237], v[72:75]
	v_mfma_f32_16x16x32_f16 v[116:119], v[172:175], v[188:191], v[116:119]
	v_mfma_f32_16x16x32_f16 v[112:115], v[180:183], v[188:191], v[112:115]
	v_mfma_f32_16x16x32_f16 v[100:103], v[172:175], v[214:217], v[100:103]
	v_mfma_f32_16x16x32_f16 v[96:99], v[180:183], v[214:217], v[96:99]
	v_mfma_f32_16x16x32_f16 v[84:87], v[172:175], v[222:225], v[84:87]
	v_mfma_f32_16x16x32_f16 v[80:83], v[180:183], v[222:225], v[80:83]
	v_mfma_f32_16x16x32_f16 v[68:71], v[172:175], v[230:233], v[68:71]
	v_mfma_f32_16x16x32_f16 v[64:67], v[180:183], v[230:233], v[64:67]
	v_mfma_f32_16x16x32_f16 v[116:119], v[176:179], v[192:195], v[116:119]
	v_mfma_f32_16x16x32_f16 v[112:115], v[184:187], v[192:195], v[112:115]
	v_mfma_f32_16x16x32_f16 v[100:103], v[176:179], v[218:221], v[100:103]
	v_mfma_f32_16x16x32_f16 v[96:99], v[184:187], v[218:221], v[96:99]
	v_mfma_f32_16x16x32_f16 v[84:87], v[176:179], v[226:229], v[84:87]
	v_mfma_f32_16x16x32_f16 v[80:83], v[184:187], v[226:229], v[80:83]
	v_mfma_f32_16x16x32_f16 v[68:71], v[176:179], v[234:237], v[68:71]
	v_mfma_f32_16x16x32_f16 v[64:67], v[184:187], v[234:237], v[64:67]
	s_setprio 0
	s_barrier
	s_add_i32 s4, s6, s23
	s_mov_b32 m0, s4
	ds_read_b128 v[188:191], v147 offset:16384
	ds_read_b128 v[192:195], v147 offset:17408
	ds_read_b128 v[214:217], v147 offset:18432
	ds_read_b128 v[218:221], v147 offset:19456
	ds_read_b128 v[222:225], v147 offset:20480
	ds_read_b128 v[226:229], v147 offset:21504
	ds_read_b128 v[230:233], v147 offset:22528
	ds_read_b128 v[234:237], v147 offset:23552
	global_load_lds_dwordx4 v160, s[68:69]
	s_add_i32 m0, s4, 0x2000
	s_add_u32 s4, s68, 0x40000
	s_addc_u32 s5, s69, 0
	s_add_i32 s6, s7, s23
	global_load_lds_dwordx4 v128, s[68:69]
	s_mov_b32 m0, s6
	s_nop 0
	global_load_lds_dwordx4 v160, s[4:5]
	s_add_i32 m0, s6, 0x2000
	s_nop 0
	global_load_lds_dwordx4 v128, s[4:5]
	s_mov_b32 m0, s24
	s_nop 0
	global_load_lds_dwordx4 v132, s[70:71]
	s_mov_b32 m0, s25
	s_nop 0
	global_load_lds_dwordx4 v130, s[70:71]
	s_waitcnt vmcnt(8)
	s_waitcnt lgkmcnt(0)
	s_barrier
	s_setprio 1
	s_waitcnt lgkmcnt(0)
	v_mfma_f32_16x16x32_f16 v[60:63], v[138:141], v[188:191], v[60:63]
	v_mfma_f32_16x16x32_f16 v[56:59], v[152:155], v[188:191], v[56:59]
	v_mfma_f32_16x16x32_f16 v[44:47], v[138:141], v[214:217], v[44:47]
	v_mfma_f32_16x16x32_f16 v[40:43], v[152:155], v[214:217], v[40:43]
	v_mfma_f32_16x16x32_f16 v[28:31], v[138:141], v[222:225], v[28:31]
	v_mfma_f32_16x16x32_f16 v[24:27], v[152:155], v[222:225], v[24:27]
	v_mfma_f32_16x16x32_f16 v[12:15], v[138:141], v[230:233], v[12:15]
	v_mfma_f32_16x16x32_f16 v[8:11], v[152:155], v[230:233], v[8:11]
	v_mfma_f32_16x16x32_f16 v[60:63], v[148:151], v[192:195], v[60:63]
	v_mfma_f32_16x16x32_f16 v[56:59], v[156:159], v[192:195], v[56:59]
	v_mfma_f32_16x16x32_f16 v[44:47], v[148:151], v[218:221], v[44:47]
	v_mfma_f32_16x16x32_f16 v[40:43], v[156:159], v[218:221], v[40:43]
	v_mfma_f32_16x16x32_f16 v[28:31], v[148:151], v[226:229], v[28:31]
	v_mfma_f32_16x16x32_f16 v[24:27], v[156:159], v[226:229], v[24:27]
	v_mfma_f32_16x16x32_f16 v[12:15], v[148:151], v[234:237], v[12:15]
	v_mfma_f32_16x16x32_f16 v[8:11], v[156:159], v[234:237], v[8:11]
	v_mfma_f32_16x16x32_f16 v[52:55], v[172:175], v[188:191], v[52:55]
	v_mfma_f32_16x16x32_f16 v[48:51], v[180:183], v[188:191], v[48:51]
	v_mfma_f32_16x16x32_f16 v[36:39], v[172:175], v[214:217], v[36:39]
	v_mfma_f32_16x16x32_f16 v[32:35], v[180:183], v[214:217], v[32:35]
	v_mfma_f32_16x16x32_f16 v[20:23], v[172:175], v[222:225], v[20:23]
	v_mfma_f32_16x16x32_f16 v[16:19], v[180:183], v[222:225], v[16:19]
	v_mfma_f32_16x16x32_f16 v[4:7], v[172:175], v[230:233], v[4:7]
	v_mfma_f32_16x16x32_f16 v[0:3], v[180:183], v[230:233], v[0:3]
	v_mfma_f32_16x16x32_f16 v[52:55], v[176:179], v[192:195], v[52:55]
	v_mfma_f32_16x16x32_f16 v[48:51], v[184:187], v[192:195], v[48:51]
	v_mfma_f32_16x16x32_f16 v[36:39], v[176:179], v[218:221], v[36:39]
	v_mfma_f32_16x16x32_f16 v[32:35], v[184:187], v[218:221], v[32:35]
	v_mfma_f32_16x16x32_f16 v[20:23], v[176:179], v[226:229], v[20:23]
	v_mfma_f32_16x16x32_f16 v[16:19], v[184:187], v[226:229], v[16:19]
	v_mfma_f32_16x16x32_f16 v[4:7], v[176:179], v[234:237], v[4:7]
	v_mfma_f32_16x16x32_f16 v[0:3], v[184:187], v[234:237], v[0:3]
	s_setprio 0
	s_barrier
; #define PG8_STAGE(bufoff, gbase, voff) do { _Pragma("unroll") for (int _i = 0; _i < 2; ++_i) \
;         __builtin_amdgcn_global_load_lds((const unsigned*)((const char*)(gbase) + (voff)[_i]), (LAS unsigned*)(lds + (bufoff) + ldsw + _i * 8192), 16, 0, 0); } while (0)
; #define PG8_LDA(dst, b, h) do { _Pragma("unroll") for (int m = 0; m < 4; ++m) _Pragma("unroll") for (int k = 0; k < 2; ++k) dst[m][k] = *(const LAS bf16x8*)(lds + PG8_SA(b, h) + aoff + m * 2048 + k * 1024); } while (0)
; #define PG8_LDB(dst, b, h) do { _Pragma("unroll") for (int n = 0; n < 2; ++n) _Pragma("unroll") for (int k = 0; k < 2; ++k) dst[n][k] = *(const LAS bf16x8*)(lds + PG8_SB(b, h) + boff + n * 2048 + k * 1024); } while (0)
; #define PG8_WAIT_V(n) asm volatile("s_waitcnt vmcnt(" #n ")" ::: "memory")
; #define PG8_WAIT_L(n) asm volatile("s_waitcnt lgkmcnt(" #n ")" ::: "memory")
; #define PG8_BAR __builtin_amdgcn_s_barrier()
; #define PG8_SCHED __builtin_amdgcn_sched_barrier(0)
; template <class Epi>
; __device__ __forceinline__ void gemm_phase(LAS unsigned char* lds, const Gemm g, const Order& S, const Epi& E) {
;     ...
;             PG8_LDB(B0, 1, 0); PG8_LDB(B1, 1, 1); PG8_SCHED; PG8_LDA(At, 1, 0); PG8_STAGE(PG8_SA(0, 1), a2 + hstepA, voffA);
;             PG8_WAIT_V(8); PG8_WAIT_L(0); PG8_BAR; PG8_MMA(0, 0, At, B0); PG8_MMA(0, 1, At, B1); PG8_BAR; PG8_SCHED;
;             PG8_LDA(At, 1, 1); PG8_STAGE(PG8_SB(1, 0), b3, voffB); PG8_STAGE(PG8_SB(1, 1), b3 + hstepB, voffB); PG8_STAGE(PG8_SA(1, 0), a3, voffA);
;             PG8_WAIT_V(8); PG8_WAIT_L(0); PG8_BAR; PG8_MMA(1, 0, At, B0); PG8_MMA(1, 1, At, B1); PG8_BAR; PG8_SCHED;
;         }
;         if constexpr (ALIGN_EPI) { if (wr == 0) PG8_BAR; }
	s_add_i32 s6, 0, 0x18000
	s_add_i32 s7, 0, 0x1c000
	v_add_u32_e32 v156, s6, v145
	v_add_u32_e32 v171, s7, v145
	ds_read_b128 v[138:141], v156
	ds_read_b128 v[148:151], v156 offset:1024
	ds_read_b128 v[152:155], v156 offset:2048
	ds_read_b128 v[156:159], v156 offset:3072
	ds_read_b128 v[172:175], v171
	ds_read_b128 v[176:179], v171 offset:1024
	ds_read_b128 v[180:183], v171 offset:2048
	ds_read_b128 v[184:187], v171 offset:3072
	s_add_u32 s4, s70, 0x40000
	s_addc_u32 s5, s71, 0
	s_mov_b32 m0, s26
	ds_read_b128 v[188:191], v147 offset:32768
	ds_read_b128 v[192:195], v147 offset:33792
	ds_read_b128 v[214:217], v147 offset:34816
	ds_read_b128 v[218:221], v147 offset:35840
	ds_read_b128 v[222:225], v147 offset:36864
	ds_read_b128 v[226:229], v147 offset:37888
	ds_read_b128 v[230:233], v147 offset:38912
	ds_read_b128 v[234:237], v147 offset:39936
	global_load_lds_dwordx4 v132, s[4:5]
	s_mov_b32 m0, s27
	s_nop 0
	global_load_lds_dwordx4 v130, s[4:5]
	s_waitcnt vmcnt(8)
	s_waitcnt lgkmcnt(0)
	s_barrier
	s_setprio 1
	s_waitcnt lgkmcnt(0)
	v_mfma_f32_16x16x32_f16 v[124:127], v[138:141], v[188:191], v[124:127]
	v_mfma_f32_16x16x32_f16 v[120:123], v[152:155], v[188:191], v[120:123]
	v_mfma_f32_16x16x32_f16 v[108:111], v[138:141], v[214:217], v[108:111]
	v_mfma_f32_16x16x32_f16 v[104:107], v[152:155], v[214:217], v[104:107]
	v_mfma_f32_16x16x32_f16 v[92:95], v[138:141], v[222:225], v[92:95]
	v_mfma_f32_16x16x32_f16 v[88:91], v[152:155], v[222:225], v[88:91]
	v_mfma_f32_16x16x32_f16 v[76:79], v[138:141], v[230:233], v[76:79]
	v_mfma_f32_16x16x32_f16 v[72:75], v[152:155], v[230:233], v[72:75]
	v_mfma_f32_16x16x32_f16 v[124:127], v[148:151], v[192:195], v[124:127]
	v_mfma_f32_16x16x32_f16 v[120:123], v[156:159], v[192:195], v[120:123]
	v_mfma_f32_16x16x32_f16 v[108:111], v[148:151], v[218:221], v[108:111]
	v_mfma_f32_16x16x32_f16 v[104:107], v[156:159], v[218:221], v[104:107]
	v_mfma_f32_16x16x32_f16 v[92:95], v[148:151], v[226:229], v[92:95]
	v_mfma_f32_16x16x32_f16 v[88:91], v[156:159], v[226:229], v[88:91]
	v_mfma_f32_16x16x32_f16 v[76:79], v[148:151], v[234:237], v[76:79]
	v_mfma_f32_16x16x32_f16 v[72:75], v[156:159], v[234:237], v[72:75]
	v_mfma_f32_16x16x32_f16 v[116:119], v[172:175], v[188:191], v[116:119]
	v_mfma_f32_16x16x32_f16 v[112:115], v[180:183], v[188:191], v[112:115]
	v_mfma_f32_16x16x32_f16 v[100:103], v[172:175], v[214:217], v[100:103]
	v_mfma_f32_16x16x32_f16 v[96:99], v[180:183], v[214:217], v[96:99]
	v_mfma_f32_16x16x32_f16 v[84:87], v[172:175], v[222:225], v[84:87]
	v_mfma_f32_16x16x32_f16 v[80:83], v[180:183], v[222:225], v[80:83]
	v_mfma_f32_16x16x32_f16 v[68:71], v[172:175], v[230:233], v[68:71]
	v_mfma_f32_16x16x32_f16 v[64:67], v[180:183], v[230:233], v[64:67]
	v_mfma_f32_16x16x32_f16 v[116:119], v[176:179], v[192:195], v[116:119]
	v_mfma_f32_16x16x32_f16 v[112:115], v[184:187], v[192:195], v[112:115]
	v_mfma_f32_16x16x32_f16 v[100:103], v[176:179], v[218:221], v[100:103]
	v_mfma_f32_16x16x32_f16 v[96:99], v[184:187], v[218:221], v[96:99]
	v_mfma_f32_16x16x32_f16 v[84:87], v[176:179], v[226:229], v[84:87]
	v_mfma_f32_16x16x32_f16 v[80:83], v[184:187], v[226:229], v[80:83]
	v_mfma_f32_16x16x32_f16 v[68:71], v[176:179], v[234:237], v[68:71]
	v_mfma_f32_16x16x32_f16 v[64:67], v[184:187], v[234:237], v[64:67]
	s_setprio 0
	s_barrier
	s_add_i32 s4, s6, s23
	s_add_u32 s100, s68, 0x80
	s_addc_u32 s101, s69, 0
	s_mov_b32 m0, s4
	ds_read_b128 v[188:191], v147 offset:49152
	ds_read_b128 v[192:195], v147 offset:50176
	ds_read_b128 v[214:217], v147 offset:51200
	ds_read_b128 v[218:221], v147 offset:52224
	ds_read_b128 v[222:225], v147 offset:53248
	ds_read_b128 v[226:229], v147 offset:54272
	ds_read_b128 v[230:233], v147 offset:55296
	ds_read_b128 v[234:237], v147 offset:56320
	global_load_lds_dwordx4 v160, s[100:101]
	s_add_i32 m0, s4, 0x2000
	s_add_u32 s4, s68, 0x40080
	s_addc_u32 s5, s69, 0
	s_add_i32 s6, s7, s23
	global_load_lds_dwordx4 v128, s[100:101]
	s_mov_b32 m0, s6
	s_nop 0
	global_load_lds_dwordx4 v160, s[4:5]
	s_add_i32 m0, s6, 0x2000
	s_nop 0
	global_load_lds_dwordx4 v128, s[4:5]
	s_add_u32 s100, s70, 0x80
	s_addc_u32 s101, s71, 0
	s_mov_b32 m0, s28
	s_nop 0
	global_load_lds_dwordx4 v132, s[100:101]
	s_mov_b32 m0, s29
	s_nop 0
	global_load_lds_dwordx4 v130, s[100:101]
	s_waitcnt vmcnt(8)
	s_waitcnt lgkmcnt(0)
	s_barrier
	s_setprio 1
	s_waitcnt lgkmcnt(0)
	v_mfma_f32_16x16x32_f16 v[60:63], v[138:141], v[188:191], v[60:63]
	v_mfma_f32_16x16x32_f16 v[56:59], v[152:155], v[188:191], v[56:59]
	v_mfma_f32_16x16x32_f16 v[44:47], v[138:141], v[214:217], v[44:47]
	v_mfma_f32_16x16x32_f16 v[40:43], v[152:155], v[214:217], v[40:43]
	v_mfma_f32_16x16x32_f16 v[28:31], v[138:141], v[222:225], v[28:31]
	v_mfma_f32_16x16x32_f16 v[24:27], v[152:155], v[222:225], v[24:27]
	v_mfma_f32_16x16x32_f16 v[12:15], v[138:141], v[230:233], v[12:15]
	v_mfma_f32_16x16x32_f16 v[8:11], v[152:155], v[230:233], v[8:11]
	v_mfma_f32_16x16x32_f16 v[60:63], v[148:151], v[192:195], v[60:63]
	v_mfma_f32_16x16x32_f16 v[56:59], v[156:159], v[192:195], v[56:59]
	v_mfma_f32_16x16x32_f16 v[44:47], v[148:151], v[218:221], v[44:47]
	v_mfma_f32_16x16x32_f16 v[40:43], v[156:159], v[218:221], v[40:43]
	v_mfma_f32_16x16x32_f16 v[28:31], v[148:151], v[226:229], v[28:31]
	v_mfma_f32_16x16x32_f16 v[24:27], v[156:159], v[226:229], v[24:27]
	v_mfma_f32_16x16x32_f16 v[12:15], v[148:151], v[234:237], v[12:15]
	v_mfma_f32_16x16x32_f16 v[8:11], v[156:159], v[234:237], v[8:11]
	v_mfma_f32_16x16x32_f16 v[52:55], v[172:175], v[188:191], v[52:55]
	v_mfma_f32_16x16x32_f16 v[48:51], v[180:183], v[188:191], v[48:51]
	v_mfma_f32_16x16x32_f16 v[36:39], v[172:175], v[214:217], v[36:39]
	v_mfma_f32_16x16x32_f16 v[32:35], v[180:183], v[214:217], v[32:35]
	v_mfma_f32_16x16x32_f16 v[20:23], v[172:175], v[222:225], v[20:23]
	v_mfma_f32_16x16x32_f16 v[16:19], v[180:183], v[222:225], v[16:19]
	v_mfma_f32_16x16x32_f16 v[4:7], v[172:175], v[230:233], v[4:7]
	v_mfma_f32_16x16x32_f16 v[0:3], v[180:183], v[230:233], v[0:3]
	v_mfma_f32_16x16x32_f16 v[52:55], v[176:179], v[192:195], v[52:55]
	v_mfma_f32_16x16x32_f16 v[48:51], v[184:187], v[192:195], v[48:51]
	v_mfma_f32_16x16x32_f16 v[36:39], v[176:179], v[218:221], v[36:39]
	v_mfma_f32_16x16x32_f16 v[32:35], v[184:187], v[218:221], v[32:35]
	v_mfma_f32_16x16x32_f16 v[20:23], v[176:179], v[226:229], v[20:23]
	v_mfma_f32_16x16x32_f16 v[16:19], v[184:187], v[226:229], v[16:19]
	v_mfma_f32_16x16x32_f16 v[4:7], v[176:179], v[234:237], v[4:7]
	v_mfma_f32_16x16x32_f16 v[0:3], v[184:187], v[234:237], v[0:3]
	s_setprio 0
	s_barrier
	s_add_i32 vcc_lo, vcc_lo, 2
	s_add_u32 s40, s40, 0x100
	s_addc_u32 s41, s41, 0
	s_add_u32 s88, s88, 0x100
	s_addc_u32 s89, s89, 0
	s_cmp_gt_u32 vcc_lo, 13
	s_cbranch_scc0 .LBB0_81
	s_and_b64 vcc, exec, s[42:43]
	s_cbranch_vccz .LBB0_84
	s_barrier

; #define PG8_STAGE(bufoff, gbase, voff) do { _Pragma("unroll") for (int _i = 0; _i < 2; ++_i) \
;         __builtin_amdgcn_global_load_lds((const unsigned*)((const char*)(gbase) + (voff)[_i]), (LAS unsigned*)(lds + (bufoff) + ldsw + _i * 8192), 16, 0, 0); } while (0)
; #define PG8_LDA(dst, b, h) do { _Pragma("unroll") for (int m = 0; m < 4; ++m) _Pragma("unroll") for (int k = 0; k < 2; ++k) dst[m][k] = *(const LAS bf16x8*)(lds + PG8_SA(b, h) + aoff + m * 2048 + k * 1024); } while (0)
; #define PG8_LDB(dst, b, h) do { _Pragma("unroll") for (int n = 0; n < 2; ++n) _Pragma("unroll") for (int k = 0; k < 2; ++k) dst[n][k] = *(const LAS bf16x8*)(lds + PG8_SB(b, h) + boff + n * 2048 + k * 1024); } while (0)
; #define PG8_WAIT_V(n) asm volatile("s_waitcnt vmcnt(" #n ")" ::: "memory")
; #define PG8_WAIT_L(n) asm volatile("s_waitcnt lgkmcnt(" #n ")" ::: "memory")
; #define PG8_BAR __builtin_amdgcn_s_barrier()
; #define PG8_SCHED __builtin_amdgcn_sched_barrier(0)
; template <class Epi>
; __device__ __forceinline__ void gemm_phase(LAS unsigned char* lds, const Gemm g, const Order& S, const Epi& E) {
;     ...
;         const bool has_next = S.next(ui + 1, nxt);
;         const char* nA = has_next ? (const char*)(g.A + (size_t)nxt.pm * BM * g.lda + (size_t)nxt.z * g.za) : cA;
;         const char* nB = has_next ? (const char*)(g.Bt + (size_t)nxt.pn * BM * g.ldb + (size_t)nxt.z * g.zb) : cB;
;         for (int t = 0; t < nt; t += 2) {
;             const bool last = (t == nt - 2);
;             const char* a1 = cA + (size_t)(t + 1) * kstep;
;             const char* a2 = last ? nA : cA + (size_t)(t + 2) * kstep; const char* b2 = last ? nB : cB + (size_t)(t + 2) * kstep;
;             const char* a3 = a2 + kstep; const char* b3 = b2 + kstep;
;             PG8_LDB(B0, 0, 0); PG8_LDB(B1, 0, 1); PG8_SCHED; PG8_LDA(At, 0, 0); PG8_STAGE(PG8_SA(1, 1), a1 + hstepA, voffA);
;             PG8_WAIT_V(8); PG8_WAIT_L(0); PG8_BAR; PG8_MMA(0, 0, At, B0); PG8_MMA(0, 1, At, B1); PG8_BAR; PG8_SCHED;
;             PG8_LDA(At, 0, 1); PG8_STAGE(PG8_SB(0, 0), b2, voffB); PG8_STAGE(PG8_SB(0, 1), b2 + hstepB, voffB); PG8_STAGE(PG8_SA(0, 0), a2, voffA);
;             PG8_WAIT_V(8); PG8_WAIT_L(0); PG8_BAR; PG8_MMA(1, 0, At, B0); PG8_MMA(1, 1, At, B1); PG8_BAR; PG8_SCHED;
.LBB0_281:
	s_add_u32 s40, s64, 0x100
	s_addc_u32 s41, s65, 0
	s_add_i32 s4, 0, 0x10000
	s_cmp_eq_u32 s47, 4
	s_cselect_b32 s69, s49, s41
	s_cselect_b32 s68, s48, s40
	s_cselect_b32 s67, s34, s45
	s_cselect_b32 s66, s35, s43
	s_add_i32 s6, 0, 0x14000
	v_add_u32_e32 v150, s4, v184
	v_add_u32_e32 v158, s6, v184
	ds_read_b128 v[138:141], v150
	ds_read_b128 v[142:145], v150 offset:1024
	ds_read_b128 v[146:149], v150 offset:2048
	ds_read_b128 v[150:153], v150 offset:3072
	ds_read_b128 v[154:157], v158
	ds_read_b128 v[172:175], v158 offset:1024
	ds_read_b128 v[176:179], v158 offset:2048
	ds_read_b128 v[180:183], v158 offset:3072
	s_add_i32 m0, s25, 0xc000
	ds_read_b128 v[188:191], v186
	ds_read_b128 v[192:195], v186 offset:1024
	ds_read_b128 v[214:217], v186 offset:2048
	ds_read_b128 v[218:221], v186 offset:3072
	ds_read_b128 v[222:225], v186 offset:4096
	ds_read_b128 v[226:229], v186 offset:5120
	ds_read_b128 v[230:233], v186 offset:6144
	ds_read_b128 v[234:237], v186 offset:7168
	global_load_lds_dwordx4 v134, s[64:65]
	s_add_i32 m0, s25, 0xe000
	s_nop 0
	global_load_lds_dwordx4 v136, s[64:65]
	s_waitcnt vmcnt(8)
	s_waitcnt lgkmcnt(0)
	s_barrier
	s_setprio 1
	s_waitcnt lgkmcnt(0)
	v_mfma_f32_16x16x32_bf16 v[124:127], v[138:141], v[188:191], v[124:127]
	v_mfma_f32_16x16x32_bf16 v[120:123], v[146:149], v[188:191], v[120:123]
	v_mfma_f32_16x16x32_bf16 v[116:119], v[138:141], v[214:217], v[116:119]
	v_mfma_f32_16x16x32_bf16 v[112:115], v[146:149], v[214:217], v[112:115]
	v_mfma_f32_16x16x32_bf16 v[108:111], v[138:141], v[222:225], v[108:111]
	v_mfma_f32_16x16x32_bf16 v[104:107], v[146:149], v[222:225], v[104:107]
	v_mfma_f32_16x16x32_bf16 v[100:103], v[138:141], v[230:233], v[100:103]
	v_mfma_f32_16x16x32_bf16 v[96:99], v[146:149], v[230:233], v[96:99]
	v_mfma_f32_16x16x32_bf16 v[124:127], v[142:145], v[192:195], v[124:127]
	v_mfma_f32_16x16x32_bf16 v[120:123], v[150:153], v[192:195], v[120:123]
	v_mfma_f32_16x16x32_bf16 v[116:119], v[142:145], v[218:221], v[116:119]
	v_mfma_f32_16x16x32_bf16 v[112:115], v[150:153], v[218:221], v[112:115]
	v_mfma_f32_16x16x32_bf16 v[108:111], v[142:145], v[226:229], v[108:111]
	v_mfma_f32_16x16x32_bf16 v[104:107], v[150:153], v[226:229], v[104:107]
	v_mfma_f32_16x16x32_bf16 v[100:103], v[142:145], v[234:237], v[100:103]
	v_mfma_f32_16x16x32_bf16 v[96:99], v[150:153], v[234:237], v[96:99]
	v_mfma_f32_16x16x32_bf16 v[92:95], v[154:157], v[188:191], v[92:95]
	v_mfma_f32_16x16x32_bf16 v[88:91], v[176:179], v[188:191], v[88:91]
	v_mfma_f32_16x16x32_bf16 v[84:87], v[154:157], v[214:217], v[84:87]
	v_mfma_f32_16x16x32_bf16 v[80:83], v[176:179], v[214:217], v[80:83]
	v_mfma_f32_16x16x32_bf16 v[76:79], v[154:157], v[222:225], v[76:79]
	v_mfma_f32_16x16x32_bf16 v[72:75], v[176:179], v[222:225], v[72:75]
	v_mfma_f32_16x16x32_bf16 v[68:71], v[154:157], v[230:233], v[68:71]
	v_mfma_f32_16x16x32_bf16 v[64:67], v[176:179], v[230:233], v[64:67]
	v_mfma_f32_16x16x32_bf16 v[92:95], v[172:175], v[192:195], v[92:95]
	v_mfma_f32_16x16x32_bf16 v[88:91], v[180:183], v[192:195], v[88:91]
	v_mfma_f32_16x16x32_bf16 v[84:87], v[172:175], v[218:221], v[84:87]
	v_mfma_f32_16x16x32_bf16 v[80:83], v[180:183], v[218:221], v[80:83]
	v_mfma_f32_16x16x32_bf16 v[76:79], v[172:175], v[226:229], v[76:79]
	v_mfma_f32_16x16x32_bf16 v[72:75], v[180:183], v[226:229], v[72:75]
	v_mfma_f32_16x16x32_bf16 v[68:71], v[172:175], v[234:237], v[68:71]
	v_mfma_f32_16x16x32_bf16 v[64:67], v[180:183], v[234:237], v[64:67]
	s_setprio 0
	s_barrier
	s_add_i32 s4, s4, s24
	s_mov_b32 m0, s4
	ds_read_b128 v[188:191], v186 offset:16384
	ds_read_b128 v[192:195], v186 offset:17408
	ds_read_b128 v[214:217], v186 offset:18432
	ds_read_b128 v[218:221], v186 offset:19456
	ds_read_b128 v[222:225], v186 offset:20480
	ds_read_b128 v[226:229], v186 offset:21504
	ds_read_b128 v[230:233], v186 offset:22528
	ds_read_b128 v[234:237], v186 offset:23552
	global_load_lds_dwordx4 v160, s[66:67]
	s_add_i32 m0, s4, 0x2000
	s_add_u32 s4, s66, 0x20000
	s_addc_u32 s5, s67, 0
	s_add_i32 s6, s6, s24
	global_load_lds_dwordx4 v128, s[66:67]
	s_mov_b32 m0, s6
	s_nop 0
	global_load_lds_dwordx4 v160, s[4:5]
	s_add_i32 m0, s6, 0x2000
	s_nop 0
	global_load_lds_dwordx4 v128, s[4:5]
	s_mov_b32 m0, s25
	s_nop 0
	global_load_lds_dwordx4 v132, s[68:69]
	s_mov_b32 m0, s26
	s_nop 0
	global_load_lds_dwordx4 v130, s[68:69]
	s_waitcnt vmcnt(8)
	s_waitcnt lgkmcnt(0)
	s_barrier
	s_setprio 1
	s_waitcnt lgkmcnt(0)
	v_mfma_f32_16x16x32_bf16 v[60:63], v[138:141], v[188:191], v[60:63]
	v_mfma_f32_16x16x32_bf16 v[56:59], v[146:149], v[188:191], v[56:59]
	v_mfma_f32_16x16x32_bf16 v[52:55], v[138:141], v[214:217], v[52:55]
	v_mfma_f32_16x16x32_bf16 v[48:51], v[146:149], v[214:217], v[48:51]
	v_mfma_f32_16x16x32_bf16 v[44:47], v[138:141], v[222:225], v[44:47]
	v_mfma_f32_16x16x32_bf16 v[40:43], v[146:149], v[222:225], v[40:43]
	v_mfma_f32_16x16x32_bf16 v[36:39], v[138:141], v[230:233], v[36:39]
	v_mfma_f32_16x16x32_bf16 v[32:35], v[146:149], v[230:233], v[32:35]
	v_mfma_f32_16x16x32_bf16 v[60:63], v[142:145], v[192:195], v[60:63]
	v_mfma_f32_16x16x32_bf16 v[56:59], v[150:153], v[192:195], v[56:59]
	v_mfma_f32_16x16x32_bf16 v[52:55], v[142:145], v[218:221], v[52:55]
	v_mfma_f32_16x16x32_bf16 v[48:51], v[150:153], v[218:221], v[48:51]
	v_mfma_f32_16x16x32_bf16 v[44:47], v[142:145], v[226:229], v[44:47]
	v_mfma_f32_16x16x32_bf16 v[40:43], v[150:153], v[226:229], v[40:43]
	v_mfma_f32_16x16x32_bf16 v[36:39], v[142:145], v[234:237], v[36:39]
	v_mfma_f32_16x16x32_bf16 v[32:35], v[150:153], v[234:237], v[32:35]
	v_mfma_f32_16x16x32_bf16 v[28:31], v[154:157], v[188:191], v[28:31]
	v_mfma_f32_16x16x32_bf16 v[24:27], v[176:179], v[188:191], v[24:27]
	v_mfma_f32_16x16x32_bf16 v[20:23], v[154:157], v[214:217], v[20:23]
	v_mfma_f32_16x16x32_bf16 v[16:19], v[176:179], v[214:217], v[16:19]
	v_mfma_f32_16x16x32_bf16 v[12:15], v[154:157], v[222:225], v[12:15]
	v_mfma_f32_16x16x32_bf16 v[8:11], v[176:179], v[222:225], v[8:11]
	v_mfma_f32_16x16x32_bf16 v[4:7], v[154:157], v[230:233], v[4:7]
	v_mfma_f32_16x16x32_bf16 v[0:3], v[176:179], v[230:233], v[0:3]
	v_mfma_f32_16x16x32_bf16 v[28:31], v[172:175], v[192:195], v[28:31]
	v_mfma_f32_16x16x32_bf16 v[24:27], v[180:183], v[192:195], v[24:27]
	v_mfma_f32_16x16x32_bf16 v[20:23], v[172:175], v[218:221], v[20:23]
	v_mfma_f32_16x16x32_bf16 v[16:19], v[180:183], v[218:221], v[16:19]
	v_mfma_f32_16x16x32_bf16 v[12:15], v[172:175], v[226:229], v[12:15]
	v_mfma_f32_16x16x32_bf16 v[8:11], v[180:183], v[226:229], v[8:11]
	v_mfma_f32_16x16x32_bf16 v[4:7], v[172:175], v[234:237], v[4:7]
	v_mfma_f32_16x16x32_bf16 v[0:3], v[180:183], v[234:237], v[0:3]
	s_setprio 0
	s_barrier
; #define PG8_STAGE(bufoff, gbase, voff) do { _Pragma("unroll") for (int _i = 0; _i < 2; ++_i) \
;         __builtin_amdgcn_global_load_lds((const unsigned*)((const char*)(gbase) + (voff)[_i]), (LAS unsigned*)(lds + (bufoff) + ldsw + _i * 8192), 16, 0, 0); } while (0)
; #define PG8_LDA(dst, b, h) do { _Pragma("unroll") for (int m = 0; m < 4; ++m) _Pragma("unroll") for (int k = 0; k < 2; ++k) dst[m][k] = *(const LAS bf16x8*)(lds + PG8_SA(b, h) + aoff + m * 2048 + k * 1024); } while (0)
; #define PG8_LDB(dst, b, h) do { _Pragma("unroll") for (int n = 0; n < 2; ++n) _Pragma("unroll") for (int k = 0; k < 2; ++k) dst[n][k] = *(const LAS bf16x8*)(lds + PG8_SB(b, h) + boff + n * 2048 + k * 1024); } while (0)
; #define PG8_WAIT_V(n) asm volatile("s_waitcnt vmcnt(" #n ")" ::: "memory")
; #define PG8_WAIT_L(n) asm volatile("s_waitcnt lgkmcnt(" #n ")" ::: "memory")
; #define PG8_BAR __builtin_amdgcn_s_barrier()
; #define PG8_SCHED __builtin_amdgcn_sched_barrier(0)
; template <class Epi>
; __device__ __forceinline__ void gemm_phase(LAS unsigned char* lds, const Gemm g, const Order& S, const Epi& E) {
;     ...
;             PG8_LDB(B0, 1, 0); PG8_LDB(B1, 1, 1); PG8_SCHED; PG8_LDA(At, 1, 0); PG8_STAGE(PG8_SA(0, 1), a2 + hstepA, voffA);
;             PG8_WAIT_V(8); PG8_WAIT_L(0); PG8_BAR; PG8_MMA(0, 0, At, B0); PG8_MMA(0, 1, At, B1); PG8_BAR; PG8_SCHED;
;             PG8_LDA(At, 1, 1); PG8_STAGE(PG8_SB(1, 0), b3, voffB); PG8_STAGE(PG8_SB(1, 1), b3 + hstepB, voffB); PG8_STAGE(PG8_SA(1, 0), a3, voffA);
;             PG8_WAIT_V(8); PG8_WAIT_L(0); PG8_BAR; PG8_MMA(1, 0, At, B0); PG8_MMA(1, 1, At, B1); PG8_BAR; PG8_SCHED;
;         }
;         if constexpr (ALIGN_EPI) { if (wr == 0) PG8_BAR; }
;         if constexpr (!Epi::AFTER_DRAIN) E(acc, cur, wr, wc, fr, fq);
;         if (!has_next) break;
	s_add_i32 s6, 0, 0x18000
	s_add_i32 s7, 0, 0x1c000
	v_add_u32_e32 v150, s6, v184
	v_add_u32_e32 v180, s7, v184
	ds_read_b128 v[138:141], v150
	ds_read_b128 v[142:145], v150 offset:1024
	ds_read_b128 v[146:149], v150 offset:2048
	ds_read_b128 v[150:153], v150 offset:3072
	ds_read_b128 v[154:157], v180
	ds_read_b128 v[172:175], v180 offset:1024
	ds_read_b128 v[176:179], v180 offset:2048
	ds_read_b128 v[180:183], v180 offset:3072
	s_add_u32 s4, s68, 0x60000
	s_addc_u32 s5, s69, 0
	s_mov_b32 m0, s27
	ds_read_b128 v[188:191], v186 offset:32768
	ds_read_b128 v[192:195], v186 offset:33792
	ds_read_b128 v[214:217], v186 offset:34816
	ds_read_b128 v[218:221], v186 offset:35840
	ds_read_b128 v[222:225], v186 offset:36864
	ds_read_b128 v[226:229], v186 offset:37888
	ds_read_b128 v[230:233], v186 offset:38912
	ds_read_b128 v[234:237], v186 offset:39936
	global_load_lds_dwordx4 v132, s[4:5]
	s_mov_b32 m0, s28
	s_nop 0
	global_load_lds_dwordx4 v130, s[4:5]
	s_waitcnt vmcnt(8)
	s_waitcnt lgkmcnt(0)
	s_barrier
	s_setprio 1
	s_waitcnt lgkmcnt(0)
	v_mfma_f32_16x16x32_bf16 v[124:127], v[138:141], v[188:191], v[124:127]
	v_mfma_f32_16x16x32_bf16 v[120:123], v[146:149], v[188:191], v[120:123]
	v_mfma_f32_16x16x32_bf16 v[116:119], v[138:141], v[214:217], v[116:119]
	v_mfma_f32_16x16x32_bf16 v[112:115], v[146:149], v[214:217], v[112:115]
	v_mfma_f32_16x16x32_bf16 v[108:111], v[138:141], v[222:225], v[108:111]
	v_mfma_f32_16x16x32_bf16 v[104:107], v[146:149], v[222:225], v[104:107]
	v_mfma_f32_16x16x32_bf16 v[100:103], v[138:141], v[230:233], v[100:103]
	v_mfma_f32_16x16x32_bf16 v[96:99], v[146:149], v[230:233], v[96:99]
	v_mfma_f32_16x16x32_bf16 v[124:127], v[142:145], v[192:195], v[124:127]
	v_mfma_f32_16x16x32_bf16 v[120:123], v[150:153], v[192:195], v[120:123]
	v_mfma_f32_16x16x32_bf16 v[116:119], v[142:145], v[218:221], v[116:119]
	v_mfma_f32_16x16x32_bf16 v[112:115], v[150:153], v[218:221], v[112:115]
	v_mfma_f32_16x16x32_bf16 v[108:111], v[142:145], v[226:229], v[108:111]
	v_mfma_f32_16x16x32_bf16 v[104:107], v[150:153], v[226:229], v[104:107]
	v_mfma_f32_16x16x32_bf16 v[100:103], v[142:145], v[234:237], v[100:103]
	v_mfma_f32_16x16x32_bf16 v[96:99], v[150:153], v[234:237], v[96:99]
	v_mfma_f32_16x16x32_bf16 v[92:95], v[154:157], v[188:191], v[92:95]
	v_mfma_f32_16x16x32_bf16 v[88:91], v[176:179], v[188:191], v[88:91]
	v_mfma_f32_16x16x32_bf16 v[84:87], v[154:157], v[214:217], v[84:87]
	v_mfma_f32_16x16x32_bf16 v[80:83], v[176:179], v[214:217], v[80:83]
	v_mfma_f32_16x16x32_bf16 v[76:79], v[154:157], v[222:225], v[76:79]
	v_mfma_f32_16x16x32_bf16 v[72:75], v[176:179], v[222:225], v[72:75]
	v_mfma_f32_16x16x32_bf16 v[68:71], v[154:157], v[230:233], v[68:71]
	v_mfma_f32_16x16x32_bf16 v[64:67], v[176:179], v[230:233], v[64:67]
	v_mfma_f32_16x16x32_bf16 v[92:95], v[172:175], v[192:195], v[92:95]
	v_mfma_f32_16x16x32_bf16 v[88:91], v[180:183], v[192:195], v[88:91]
	v_mfma_f32_16x16x32_bf16 v[84:87], v[172:175], v[218:221], v[84:87]
	v_mfma_f32_16x16x32_bf16 v[80:83], v[180:183], v[218:221], v[80:83]
	v_mfma_f32_16x16x32_bf16 v[76:79], v[172:175], v[226:229], v[76:79]
	v_mfma_f32_16x16x32_bf16 v[72:75], v[180:183], v[226:229], v[72:75]
	v_mfma_f32_16x16x32_bf16 v[68:71], v[172:175], v[234:237], v[68:71]
	v_mfma_f32_16x16x32_bf16 v[64:67], v[180:183], v[234:237], v[64:67]
	s_setprio 0
	s_barrier
	s_add_i32 s4, s6, s24
	s_add_u32 s100, s66, 0x80
	s_addc_u32 s101, s67, 0
	s_mov_b32 m0, s4
	ds_read_b128 v[188:191], v186 offset:49152
	ds_read_b128 v[192:195], v186 offset:50176
	ds_read_b128 v[214:217], v186 offset:51200
	ds_read_b128 v[218:221], v186 offset:52224
	ds_read_b128 v[222:225], v186 offset:53248
	ds_read_b128 v[226:229], v186 offset:54272
	ds_read_b128 v[230:233], v186 offset:55296
	ds_read_b128 v[234:237], v186 offset:56320
	global_load_lds_dwordx4 v160, s[100:101]
	s_add_i32 m0, s4, 0x2000
	s_add_u32 s4, s66, 0x20080
	s_addc_u32 s5, s67, 0
	s_add_i32 s6, s7, s24
	global_load_lds_dwordx4 v128, s[100:101]
	s_mov_b32 m0, s6
	s_nop 0
	global_load_lds_dwordx4 v160, s[4:5]
	s_add_i32 m0, s6, 0x2000
	s_nop 0
	global_load_lds_dwordx4 v128, s[4:5]
	s_add_u32 s100, s68, 0x80
	s_addc_u32 s101, s69, 0
	s_mov_b32 m0, s29
	s_nop 0
	global_load_lds_dwordx4 v132, s[100:101]
	s_mov_b32 m0, s70
	s_nop 0
	global_load_lds_dwordx4 v130, s[100:101]
	s_waitcnt vmcnt(8)
	s_waitcnt lgkmcnt(0)
	s_barrier
	s_setprio 1
	s_waitcnt lgkmcnt(0)
	v_mfma_f32_16x16x32_bf16 v[60:63], v[138:141], v[188:191], v[60:63]
	v_mfma_f32_16x16x32_bf16 v[56:59], v[146:149], v[188:191], v[56:59]
	v_mfma_f32_16x16x32_bf16 v[52:55], v[138:141], v[214:217], v[52:55]
	v_mfma_f32_16x16x32_bf16 v[48:51], v[146:149], v[214:217], v[48:51]
	v_mfma_f32_16x16x32_bf16 v[44:47], v[138:141], v[222:225], v[44:47]
	v_mfma_f32_16x16x32_bf16 v[40:43], v[146:149], v[222:225], v[40:43]
	v_mfma_f32_16x16x32_bf16 v[36:39], v[138:141], v[230:233], v[36:39]
	v_mfma_f32_16x16x32_bf16 v[32:35], v[146:149], v[230:233], v[32:35]
	v_mfma_f32_16x16x32_bf16 v[60:63], v[142:145], v[192:195], v[60:63]
	v_mfma_f32_16x16x32_bf16 v[56:59], v[150:153], v[192:195], v[56:59]
	v_mfma_f32_16x16x32_bf16 v[52:55], v[142:145], v[218:221], v[52:55]
	v_mfma_f32_16x16x32_bf16 v[48:51], v[150:153], v[218:221], v[48:51]
	v_mfma_f32_16x16x32_bf16 v[44:47], v[142:145], v[226:229], v[44:47]
	v_mfma_f32_16x16x32_bf16 v[40:43], v[150:153], v[226:229], v[40:43]
	v_mfma_f32_16x16x32_bf16 v[36:39], v[142:145], v[234:237], v[36:39]
	v_mfma_f32_16x16x32_bf16 v[32:35], v[150:153], v[234:237], v[32:35]
	v_mfma_f32_16x16x32_bf16 v[28:31], v[154:157], v[188:191], v[28:31]
	v_mfma_f32_16x16x32_bf16 v[24:27], v[176:179], v[188:191], v[24:27]
	v_mfma_f32_16x16x32_bf16 v[20:23], v[154:157], v[214:217], v[20:23]
	v_mfma_f32_16x16x32_bf16 v[16:19], v[176:179], v[214:217], v[16:19]
	v_mfma_f32_16x16x32_bf16 v[12:15], v[154:157], v[222:225], v[12:15]
	v_mfma_f32_16x16x32_bf16 v[8:11], v[176:179], v[222:225], v[8:11]
	v_mfma_f32_16x16x32_bf16 v[4:7], v[154:157], v[230:233], v[4:7]
	v_mfma_f32_16x16x32_bf16 v[0:3], v[176:179], v[230:233], v[0:3]
	v_mfma_f32_16x16x32_bf16 v[28:31], v[172:175], v[192:195], v[28:31]
	v_mfma_f32_16x16x32_bf16 v[24:27], v[180:183], v[192:195], v[24:27]
	v_mfma_f32_16x16x32_bf16 v[20:23], v[172:175], v[218:221], v[20:23]
	v_mfma_f32_16x16x32_bf16 v[16:19], v[180:183], v[218:221], v[16:19]
	v_mfma_f32_16x16x32_bf16 v[12:15], v[172:175], v[226:229], v[12:15]
	v_mfma_f32_16x16x32_bf16 v[8:11], v[180:183], v[226:229], v[8:11]
	v_mfma_f32_16x16x32_bf16 v[4:7], v[172:175], v[234:237], v[4:7]
	v_mfma_f32_16x16x32_bf16 v[0:3], v[180:183], v[234:237], v[0:3]
	s_setprio 0
	s_barrier
	s_add_i32 s47, s47, 2
	s_add_u32 s43, s43, 0x100
	s_addc_u32 s45, s45, 0
	s_cmp_gt_u32 s47, 5
	s_mov_b64 s[64:65], s[40:41]
	s_cbranch_scc0 .LBB0_281
	s_and_b64 vcc, exec, s[12:13]
	s_cbranch_vccz .LBB0_284
	s_barrier

; #define PG8_STAGE(bufoff, gbase, voff) do { _Pragma("unroll") for (int _i = 0; _i < 2; ++_i) \
;         __builtin_amdgcn_global_load_lds((const unsigned*)((const char*)(gbase) + (voff)[_i]), (LAS unsigned*)(lds + (bufoff) + ldsw + _i * 8192), 16, 0, 0); } while (0)
; #define PG8_LDA(dst, b, h) do { _Pragma("unroll") for (int m = 0; m < 4; ++m) _Pragma("unroll") for (int k = 0; k < 2; ++k) dst[m][k] = *(const LAS bf16x8*)(lds + PG8_SA(b, h) + aoff + m * 2048 + k * 1024); } while (0)
; #define PG8_LDB(dst, b, h) do { _Pragma("unroll") for (int n = 0; n < 2; ++n) _Pragma("unroll") for (int k = 0; k < 2; ++k) dst[n][k] = *(const LAS bf16x8*)(lds + PG8_SB(b, h) + boff + n * 2048 + k * 1024); } while (0)
; #define PG8_WAIT_V(n) asm volatile("s_waitcnt vmcnt(" #n ")" ::: "memory")
; #define PG8_WAIT_L(n) asm volatile("s_waitcnt lgkmcnt(" #n ")" ::: "memory")
; #define PG8_BAR __builtin_amdgcn_s_barrier()
; #define PG8_SCHED __builtin_amdgcn_sched_barrier(0)
; template <class Epi>
; __device__ __forceinline__ void gemm_phase(LAS unsigned char* lds, const Gemm g, const Order& S, const Epi& E) {
;     ...
;         const bool has_next = S.next(ui + 1, nxt);
;         const char* nA = has_next ? (const char*)(g.A + (size_t)nxt.pm * BM * g.lda + (size_t)nxt.z * g.za) : cA;
;         const char* nB = has_next ? (const char*)(g.Bt + (size_t)nxt.pn * BM * g.ldb + (size_t)nxt.z * g.zb) : cB;
;         for (int t = 0; t < nt; t += 2) {
;             const bool last = (t == nt - 2);
;             const char* a1 = cA + (size_t)(t + 1) * kstep;
;             const char* a2 = last ? nA : cA + (size_t)(t + 2) * kstep; const char* b2 = last ? nB : cB + (size_t)(t + 2) * kstep;
;             const char* a3 = a2 + kstep; const char* b3 = b2 + kstep;
;             PG8_LDB(B0, 0, 0); PG8_LDB(B1, 0, 1); PG8_SCHED; PG8_LDA(At, 0, 0); PG8_STAGE(PG8_SA(1, 1), a1 + hstepA, voffA);
;             PG8_WAIT_V(8); PG8_WAIT_L(0); PG8_BAR; PG8_MMA(0, 0, At, B0); PG8_MMA(0, 1, At, B1); PG8_BAR; PG8_SCHED;
;             PG8_LDA(At, 0, 1); PG8_STAGE(PG8_SB(0, 0), b2, voffB); PG8_STAGE(PG8_SB(0, 1), b2 + hstepB, voffB); PG8_STAGE(PG8_SA(0, 0), a2, voffA);
;             PG8_WAIT_V(8); PG8_WAIT_L(0); PG8_BAR; PG8_MMA(1, 0, At, B0); PG8_MMA(1, 1, At, B1); PG8_BAR; PG8_SCHED;
.LBB0_396:
	s_add_u32 s4, s50, 0xfffc0080
	s_addc_u32 s5, s51, -1
	s_add_i32 s36, 0, 0x10000
	s_cmp_eq_u32 s71, 12
	s_cselect_b32 s67, s34, s5
	s_cselect_b32 s66, s35, s4
	v_add_u32_e32 v138, s36, v141
	s_cselect_b32 s65, s43, s70
	s_cselect_b32 s64, s45, s69
	s_add_i32 s4, 0, 0x14000
	ds_read_b128 v[144:147], v138
	ds_read_b128 v[148:151], v138 offset:1024
	ds_read_b128 v[152:155], v138 offset:2048
	ds_read_b128 v[156:159], v138 offset:3072
	v_add_u32_e32 v138, s4, v141
	ds_read_b128 v[172:175], v138
	ds_read_b128 v[176:179], v138 offset:1024
	ds_read_b128 v[180:183], v138 offset:2048
	ds_read_b128 v[184:187], v138 offset:3072
	s_add_i32 m0, s24, 0xc000
	ds_read_b128 v[188:191], v143
	ds_read_b128 v[192:195], v143 offset:1024
	ds_read_b128 v[214:217], v143 offset:2048
	ds_read_b128 v[218:221], v143 offset:3072
	ds_read_b128 v[222:225], v143 offset:4096
	ds_read_b128 v[226:229], v143 offset:5120
	ds_read_b128 v[230:233], v143 offset:6144
	ds_read_b128 v[234:237], v143 offset:7168
	global_load_lds_dwordx4 v134, s[50:51]
	s_add_i32 m0, s24, 0xe000
	s_nop 0
	global_load_lds_dwordx4 v136, s[50:51]
	s_waitcnt vmcnt(8)
	s_waitcnt lgkmcnt(0)
	s_barrier
	s_setprio 1
	s_waitcnt lgkmcnt(0)
	v_mfma_f32_16x16x32_f16 v[124:127], v[144:147], v[188:191], v[124:127]
	v_mfma_f32_16x16x32_f16 v[112:115], v[152:155], v[188:191], v[112:115]
	v_mfma_f32_16x16x32_f16 v[108:111], v[144:147], v[214:217], v[108:111]
	v_mfma_f32_16x16x32_f16 v[96:99], v[152:155], v[214:217], v[96:99]
	v_mfma_f32_16x16x32_f16 v[92:95], v[144:147], v[222:225], v[92:95]
	v_mfma_f32_16x16x32_f16 v[80:83], v[152:155], v[222:225], v[80:83]
	v_mfma_f32_16x16x32_f16 v[76:79], v[144:147], v[230:233], v[76:79]
	v_mfma_f32_16x16x32_f16 v[64:67], v[152:155], v[230:233], v[64:67]
	v_mfma_f32_16x16x32_f16 v[124:127], v[148:151], v[192:195], v[124:127]
	v_mfma_f32_16x16x32_f16 v[112:115], v[156:159], v[192:195], v[112:115]
	v_mfma_f32_16x16x32_f16 v[108:111], v[148:151], v[218:221], v[108:111]
	v_mfma_f32_16x16x32_f16 v[96:99], v[156:159], v[218:221], v[96:99]
	v_mfma_f32_16x16x32_f16 v[92:95], v[148:151], v[226:229], v[92:95]
	v_mfma_f32_16x16x32_f16 v[80:83], v[156:159], v[226:229], v[80:83]
	v_mfma_f32_16x16x32_f16 v[76:79], v[148:151], v[234:237], v[76:79]
	v_mfma_f32_16x16x32_f16 v[64:67], v[156:159], v[234:237], v[64:67]
	v_mfma_f32_16x16x32_f16 v[120:123], v[172:175], v[188:191], v[120:123]
	v_mfma_f32_16x16x32_f16 v[116:119], v[180:183], v[188:191], v[116:119]
	v_mfma_f32_16x16x32_f16 v[104:107], v[172:175], v[214:217], v[104:107]
	v_mfma_f32_16x16x32_f16 v[100:103], v[180:183], v[214:217], v[100:103]
	v_mfma_f32_16x16x32_f16 v[88:91], v[172:175], v[222:225], v[88:91]
	v_mfma_f32_16x16x32_f16 v[84:87], v[180:183], v[222:225], v[84:87]
	v_mfma_f32_16x16x32_f16 v[72:75], v[172:175], v[230:233], v[72:75]
	v_mfma_f32_16x16x32_f16 v[68:71], v[180:183], v[230:233], v[68:71]
	v_mfma_f32_16x16x32_f16 v[120:123], v[176:179], v[192:195], v[120:123]
	v_mfma_f32_16x16x32_f16 v[116:119], v[184:187], v[192:195], v[116:119]
	v_mfma_f32_16x16x32_f16 v[104:107], v[176:179], v[218:221], v[104:107]
	v_mfma_f32_16x16x32_f16 v[100:103], v[184:187], v[218:221], v[100:103]
	v_mfma_f32_16x16x32_f16 v[88:91], v[176:179], v[226:229], v[88:91]
	v_mfma_f32_16x16x32_f16 v[84:87], v[184:187], v[226:229], v[84:87]
	v_mfma_f32_16x16x32_f16 v[72:75], v[176:179], v[234:237], v[72:75]
	v_mfma_f32_16x16x32_f16 v[68:71], v[184:187], v[234:237], v[68:71]
	s_setprio 0
	s_barrier
	s_add_i32 s5, s36, s23
	s_mov_b32 m0, s5
	ds_read_b128 v[188:191], v143 offset:16384
	ds_read_b128 v[192:195], v143 offset:17408
	ds_read_b128 v[214:217], v143 offset:18432
	ds_read_b128 v[218:221], v143 offset:19456
	ds_read_b128 v[222:225], v143 offset:20480
	ds_read_b128 v[226:229], v143 offset:21504
	ds_read_b128 v[230:233], v143 offset:22528
	ds_read_b128 v[234:237], v143 offset:23552
	global_load_lds_dwordx4 v160, s[64:65]
	s_add_i32 m0, s5, 0x2000
	s_add_u32 s36, s64, 0x40000
	s_addc_u32 s37, s65, 0
	s_add_i32 s4, s4, s23
	global_load_lds_dwordx4 v128, s[64:65]
	s_mov_b32 m0, s4
	s_nop 0
	global_load_lds_dwordx4 v160, s[36:37]
	s_add_i32 m0, s4, 0x2000
	s_nop 0
	global_load_lds_dwordx4 v128, s[36:37]
	s_mov_b32 m0, s24
	s_nop 0
	global_load_lds_dwordx4 v132, s[66:67]
	s_mov_b32 m0, s25
	s_nop 0
	global_load_lds_dwordx4 v130, s[66:67]
	s_waitcnt vmcnt(8)
	s_waitcnt lgkmcnt(0)
	s_barrier
	s_setprio 1
	s_waitcnt lgkmcnt(0)
	v_mfma_f32_16x16x32_f16 v[60:63], v[144:147], v[188:191], v[60:63]
	v_mfma_f32_16x16x32_f16 v[48:51], v[152:155], v[188:191], v[48:51]
	v_mfma_f32_16x16x32_f16 v[44:47], v[144:147], v[214:217], v[44:47]
	v_mfma_f32_16x16x32_f16 v[32:35], v[152:155], v[214:217], v[32:35]
	v_mfma_f32_16x16x32_f16 v[28:31], v[144:147], v[222:225], v[28:31]
	v_mfma_f32_16x16x32_f16 v[16:19], v[152:155], v[222:225], v[16:19]
	v_mfma_f32_16x16x32_f16 v[12:15], v[144:147], v[230:233], v[12:15]
	v_mfma_f32_16x16x32_f16 v[0:3], v[152:155], v[230:233], v[0:3]
	v_mfma_f32_16x16x32_f16 v[60:63], v[148:151], v[192:195], v[60:63]
	v_mfma_f32_16x16x32_f16 v[48:51], v[156:159], v[192:195], v[48:51]
	v_mfma_f32_16x16x32_f16 v[44:47], v[148:151], v[218:221], v[44:47]
	v_mfma_f32_16x16x32_f16 v[32:35], v[156:159], v[218:221], v[32:35]
	v_mfma_f32_16x16x32_f16 v[28:31], v[148:151], v[226:229], v[28:31]
	v_mfma_f32_16x16x32_f16 v[16:19], v[156:159], v[226:229], v[16:19]
	v_mfma_f32_16x16x32_f16 v[12:15], v[148:151], v[234:237], v[12:15]
	v_mfma_f32_16x16x32_f16 v[0:3], v[156:159], v[234:237], v[0:3]
	v_mfma_f32_16x16x32_f16 v[56:59], v[172:175], v[188:191], v[56:59]
	v_mfma_f32_16x16x32_f16 v[52:55], v[180:183], v[188:191], v[52:55]
	v_mfma_f32_16x16x32_f16 v[40:43], v[172:175], v[214:217], v[40:43]
	v_mfma_f32_16x16x32_f16 v[36:39], v[180:183], v[214:217], v[36:39]
	v_mfma_f32_16x16x32_f16 v[24:27], v[172:175], v[222:225], v[24:27]
	v_mfma_f32_16x16x32_f16 v[20:23], v[180:183], v[222:225], v[20:23]
	v_mfma_f32_16x16x32_f16 v[8:11], v[172:175], v[230:233], v[8:11]
	v_mfma_f32_16x16x32_f16 v[4:7], v[180:183], v[230:233], v[4:7]
	v_mfma_f32_16x16x32_f16 v[56:59], v[176:179], v[192:195], v[56:59]
	v_mfma_f32_16x16x32_f16 v[52:55], v[184:187], v[192:195], v[52:55]
	v_mfma_f32_16x16x32_f16 v[40:43], v[176:179], v[218:221], v[40:43]
	v_mfma_f32_16x16x32_f16 v[36:39], v[184:187], v[218:221], v[36:39]
	v_mfma_f32_16x16x32_f16 v[24:27], v[176:179], v[226:229], v[24:27]
	v_mfma_f32_16x16x32_f16 v[20:23], v[184:187], v[226:229], v[20:23]
	v_mfma_f32_16x16x32_f16 v[8:11], v[176:179], v[234:237], v[8:11]
	v_mfma_f32_16x16x32_f16 v[4:7], v[184:187], v[234:237], v[4:7]
	s_setprio 0
	s_barrier
; #define PG8_STAGE(bufoff, gbase, voff) do { _Pragma("unroll") for (int _i = 0; _i < 2; ++_i) \
;         __builtin_amdgcn_global_load_lds((const unsigned*)((const char*)(gbase) + (voff)[_i]), (LAS unsigned*)(lds + (bufoff) + ldsw + _i * 8192), 16, 0, 0); } while (0)
; #define PG8_LDA(dst, b, h) do { _Pragma("unroll") for (int m = 0; m < 4; ++m) _Pragma("unroll") for (int k = 0; k < 2; ++k) dst[m][k] = *(const LAS bf16x8*)(lds + PG8_SA(b, h) + aoff + m * 2048 + k * 1024); } while (0)
; #define PG8_LDB(dst, b, h) do { _Pragma("unroll") for (int n = 0; n < 2; ++n) _Pragma("unroll") for (int k = 0; k < 2; ++k) dst[n][k] = *(const LAS bf16x8*)(lds + PG8_SB(b, h) + boff + n * 2048 + k * 1024); } while (0)
; #define PG8_WAIT_V(n) asm volatile("s_waitcnt vmcnt(" #n ")" ::: "memory")
; #define PG8_WAIT_L(n) asm volatile("s_waitcnt lgkmcnt(" #n ")" ::: "memory")
; #define PG8_BAR __builtin_amdgcn_s_barrier()
; #define PG8_SCHED __builtin_amdgcn_sched_barrier(0)
; template <class Epi>
; __device__ __forceinline__ void gemm_phase(LAS unsigned char* lds, const Gemm g, const Order& S, const Epi& E) {
;     ...
;             PG8_LDB(B0, 1, 0); PG8_LDB(B1, 1, 1); PG8_SCHED; PG8_LDA(At, 1, 0); PG8_STAGE(PG8_SA(0, 1), a2 + hstepA, voffA);
;             PG8_WAIT_V(8); PG8_WAIT_L(0); PG8_BAR; PG8_MMA(0, 0, At, B0); PG8_MMA(0, 1, At, B1); PG8_BAR; PG8_SCHED;
;             PG8_LDA(At, 1, 1); PG8_STAGE(PG8_SB(1, 0), b3, voffB); PG8_STAGE(PG8_SB(1, 1), b3 + hstepB, voffB); PG8_STAGE(PG8_SA(1, 0), a3, voffA);
;             PG8_WAIT_V(8); PG8_WAIT_L(0); PG8_BAR; PG8_MMA(1, 0, At, B0); PG8_MMA(1, 1, At, B1); PG8_BAR; PG8_SCHED;
;         }
;         if constexpr (ALIGN_EPI) { if (wr == 0) PG8_BAR; }
;         if constexpr (!Epi::AFTER_DRAIN) E(acc, cur, wr, wc, fr, fq);
;         if (!has_next) break;
	s_add_i32 s4, 0, 0x18000
	s_add_i32 s5, 0, 0x1c000
	v_add_u32_e32 v156, s4, v141
	v_add_u32_e32 v171, s5, v141
	ds_read_b128 v[144:147], v156
	ds_read_b128 v[148:151], v156 offset:1024
	ds_read_b128 v[152:155], v156 offset:2048
	ds_read_b128 v[156:159], v156 offset:3072
	ds_read_b128 v[172:175], v171
	ds_read_b128 v[176:179], v171 offset:1024
	ds_read_b128 v[180:183], v171 offset:2048
	ds_read_b128 v[184:187], v171 offset:3072
	s_add_u32 s36, s66, 0x40000
	s_addc_u32 s37, s67, 0
	s_mov_b32 m0, s26
	ds_read_b128 v[188:191], v143 offset:32768
	ds_read_b128 v[192:195], v143 offset:33792
	ds_read_b128 v[214:217], v143 offset:34816
	ds_read_b128 v[218:221], v143 offset:35840
	ds_read_b128 v[222:225], v143 offset:36864
	ds_read_b128 v[226:229], v143 offset:37888
	ds_read_b128 v[230:233], v143 offset:38912
	ds_read_b128 v[234:237], v143 offset:39936
	global_load_lds_dwordx4 v132, s[36:37]
	s_mov_b32 m0, s27
	s_nop 0
	global_load_lds_dwordx4 v130, s[36:37]
	s_waitcnt vmcnt(8)
	s_waitcnt lgkmcnt(0)
	s_barrier
	s_setprio 1
	s_waitcnt lgkmcnt(0)
	v_mfma_f32_16x16x32_f16 v[124:127], v[144:147], v[188:191], v[124:127]
	v_mfma_f32_16x16x32_f16 v[112:115], v[152:155], v[188:191], v[112:115]
	v_mfma_f32_16x16x32_f16 v[108:111], v[144:147], v[214:217], v[108:111]
	v_mfma_f32_16x16x32_f16 v[96:99], v[152:155], v[214:217], v[96:99]
	v_mfma_f32_16x16x32_f16 v[92:95], v[144:147], v[222:225], v[92:95]
	v_mfma_f32_16x16x32_f16 v[80:83], v[152:155], v[222:225], v[80:83]
	v_mfma_f32_16x16x32_f16 v[76:79], v[144:147], v[230:233], v[76:79]
	v_mfma_f32_16x16x32_f16 v[64:67], v[152:155], v[230:233], v[64:67]
	v_mfma_f32_16x16x32_f16 v[124:127], v[148:151], v[192:195], v[124:127]
	v_mfma_f32_16x16x32_f16 v[112:115], v[156:159], v[192:195], v[112:115]
	v_mfma_f32_16x16x32_f16 v[108:111], v[148:151], v[218:221], v[108:111]
	v_mfma_f32_16x16x32_f16 v[96:99], v[156:159], v[218:221], v[96:99]
	v_mfma_f32_16x16x32_f16 v[92:95], v[148:151], v[226:229], v[92:95]
	v_mfma_f32_16x16x32_f16 v[80:83], v[156:159], v[226:229], v[80:83]
	v_mfma_f32_16x16x32_f16 v[76:79], v[148:151], v[234:237], v[76:79]
	v_mfma_f32_16x16x32_f16 v[64:67], v[156:159], v[234:237], v[64:67]
	v_mfma_f32_16x16x32_f16 v[120:123], v[172:175], v[188:191], v[120:123]
	v_mfma_f32_16x16x32_f16 v[116:119], v[180:183], v[188:191], v[116:119]
	v_mfma_f32_16x16x32_f16 v[104:107], v[172:175], v[214:217], v[104:107]
	v_mfma_f32_16x16x32_f16 v[100:103], v[180:183], v[214:217], v[100:103]
	v_mfma_f32_16x16x32_f16 v[88:91], v[172:175], v[222:225], v[88:91]
	v_mfma_f32_16x16x32_f16 v[84:87], v[180:183], v[222:225], v[84:87]
	v_mfma_f32_16x16x32_f16 v[72:75], v[172:175], v[230:233], v[72:75]
	v_mfma_f32_16x16x32_f16 v[68:71], v[180:183], v[230:233], v[68:71]
	v_mfma_f32_16x16x32_f16 v[120:123], v[176:179], v[192:195], v[120:123]
	v_mfma_f32_16x16x32_f16 v[116:119], v[184:187], v[192:195], v[116:119]
	v_mfma_f32_16x16x32_f16 v[104:107], v[176:179], v[218:221], v[104:107]
	v_mfma_f32_16x16x32_f16 v[100:103], v[184:187], v[218:221], v[100:103]
	v_mfma_f32_16x16x32_f16 v[88:91], v[176:179], v[226:229], v[88:91]
	v_mfma_f32_16x16x32_f16 v[84:87], v[184:187], v[226:229], v[84:87]
	v_mfma_f32_16x16x32_f16 v[72:75], v[176:179], v[234:237], v[72:75]
	v_mfma_f32_16x16x32_f16 v[68:71], v[184:187], v[234:237], v[68:71]
	s_setprio 0
	s_barrier
	s_add_i32 s4, s4, s23
	s_add_u32 s100, s64, 0x80
	s_addc_u32 s101, s65, 0
	s_mov_b32 m0, s4
	ds_read_b128 v[188:191], v143 offset:49152
	ds_read_b128 v[192:195], v143 offset:50176
	ds_read_b128 v[214:217], v143 offset:51200
	ds_read_b128 v[218:221], v143 offset:52224
	ds_read_b128 v[222:225], v143 offset:53248
	ds_read_b128 v[226:229], v143 offset:54272
	ds_read_b128 v[230:233], v143 offset:55296
	ds_read_b128 v[234:237], v143 offset:56320
	global_load_lds_dwordx4 v160, s[100:101]
	s_add_i32 m0, s4, 0x2000
	s_add_u32 s36, s64, 0x40080
	s_addc_u32 s37, s65, 0
	s_add_i32 s4, s5, s23
	global_load_lds_dwordx4 v128, s[100:101]
	s_mov_b32 m0, s4
	s_nop 0
	global_load_lds_dwordx4 v160, s[36:37]
	s_add_i32 m0, s4, 0x2000
	s_nop 0
	global_load_lds_dwordx4 v128, s[36:37]
	s_add_u32 s100, s66, 0x80
	s_addc_u32 s101, s67, 0
	s_mov_b32 m0, s28
	s_nop 0
	global_load_lds_dwordx4 v132, s[100:101]
	s_mov_b32 m0, s29
	s_nop 0
	global_load_lds_dwordx4 v130, s[100:101]
	s_waitcnt vmcnt(8)
	s_waitcnt lgkmcnt(0)
	s_barrier
	s_setprio 1
	s_waitcnt lgkmcnt(0)
	v_mfma_f32_16x16x32_f16 v[60:63], v[144:147], v[188:191], v[60:63]
	v_mfma_f32_16x16x32_f16 v[48:51], v[152:155], v[188:191], v[48:51]
	v_mfma_f32_16x16x32_f16 v[44:47], v[144:147], v[214:217], v[44:47]
	v_mfma_f32_16x16x32_f16 v[32:35], v[152:155], v[214:217], v[32:35]
	v_mfma_f32_16x16x32_f16 v[28:31], v[144:147], v[222:225], v[28:31]
	v_mfma_f32_16x16x32_f16 v[16:19], v[152:155], v[222:225], v[16:19]
	v_mfma_f32_16x16x32_f16 v[12:15], v[144:147], v[230:233], v[12:15]
	v_mfma_f32_16x16x32_f16 v[0:3], v[152:155], v[230:233], v[0:3]
	v_mfma_f32_16x16x32_f16 v[60:63], v[148:151], v[192:195], v[60:63]
	v_mfma_f32_16x16x32_f16 v[48:51], v[156:159], v[192:195], v[48:51]
	v_mfma_f32_16x16x32_f16 v[44:47], v[148:151], v[218:221], v[44:47]
	v_mfma_f32_16x16x32_f16 v[32:35], v[156:159], v[218:221], v[32:35]
	v_mfma_f32_16x16x32_f16 v[28:31], v[148:151], v[226:229], v[28:31]
	v_mfma_f32_16x16x32_f16 v[16:19], v[156:159], v[226:229], v[16:19]
	v_mfma_f32_16x16x32_f16 v[12:15], v[148:151], v[234:237], v[12:15]
	v_mfma_f32_16x16x32_f16 v[0:3], v[156:159], v[234:237], v[0:3]
	v_mfma_f32_16x16x32_f16 v[56:59], v[172:175], v[188:191], v[56:59]
	v_mfma_f32_16x16x32_f16 v[52:55], v[180:183], v[188:191], v[52:55]
	v_mfma_f32_16x16x32_f16 v[40:43], v[172:175], v[214:217], v[40:43]
	v_mfma_f32_16x16x32_f16 v[36:39], v[180:183], v[214:217], v[36:39]
	v_mfma_f32_16x16x32_f16 v[24:27], v[172:175], v[222:225], v[24:27]
	v_mfma_f32_16x16x32_f16 v[20:23], v[180:183], v[222:225], v[20:23]
	v_mfma_f32_16x16x32_f16 v[8:11], v[172:175], v[230:233], v[8:11]
	v_mfma_f32_16x16x32_f16 v[4:7], v[180:183], v[230:233], v[4:7]
	v_mfma_f32_16x16x32_f16 v[56:59], v[176:179], v[192:195], v[56:59]
	v_mfma_f32_16x16x32_f16 v[52:55], v[184:187], v[192:195], v[52:55]
	v_mfma_f32_16x16x32_f16 v[40:43], v[176:179], v[218:221], v[40:43]
	v_mfma_f32_16x16x32_f16 v[36:39], v[184:187], v[218:221], v[36:39]
	v_mfma_f32_16x16x32_f16 v[24:27], v[176:179], v[226:229], v[24:27]
	v_mfma_f32_16x16x32_f16 v[20:23], v[184:187], v[226:229], v[20:23]
	v_mfma_f32_16x16x32_f16 v[8:11], v[176:179], v[234:237], v[8:11]
	v_mfma_f32_16x16x32_f16 v[4:7], v[184:187], v[234:237], v[4:7]
	s_setprio 0
	s_barrier
	s_add_i32 s71, s71, 2
	s_add_u32 s50, s50, 0x100
	s_addc_u32 s51, s51, 0
	s_add_u32 s69, s69, 0x100
	s_addc_u32 s70, s70, 0
	s_cmp_gt_u32 s71, 13
	s_cbranch_scc0 .LBB0_396
	s_and_b64 vcc, exec, s[40:41]
	s_cbranch_vccz .LBB0_399
	s_barrier

; #define PG8_STAGE(bufoff, gbase, voff) do { _Pragma("unroll") for (int _i = 0; _i < 2; ++_i) \
;         __builtin_amdgcn_global_load_lds((const unsigned*)((const char*)(gbase) + (voff)[_i]), (LAS unsigned*)(lds + (bufoff) + ldsw + _i * 8192), 16, 0, 0); } while (0)
; #define PG8_LDA(dst, b, h) do { _Pragma("unroll") for (int m = 0; m < 4; ++m) _Pragma("unroll") for (int k = 0; k < 2; ++k) dst[m][k] = *(const LAS bf16x8*)(lds + PG8_SA(b, h) + aoff + m * 2048 + k * 1024); } while (0)
; #define PG8_LDB(dst, b, h) do { _Pragma("unroll") for (int n = 0; n < 2; ++n) _Pragma("unroll") for (int k = 0; k < 2; ++k) dst[n][k] = *(const LAS bf16x8*)(lds + PG8_SB(b, h) + boff + n * 2048 + k * 1024); } while (0)
; #define PG8_WAIT_V(n) asm volatile("s_waitcnt vmcnt(" #n ")" ::: "memory")
; #define PG8_WAIT_L(n) asm volatile("s_waitcnt lgkmcnt(" #n ")" ::: "memory")
; #define PG8_BAR __builtin_amdgcn_s_barrier()
; #define PG8_SCHED __builtin_amdgcn_sched_barrier(0)
; template <class Epi>
; __device__ __forceinline__ void gemm_phase(LAS unsigned char* lds, const Gemm g, const Order& S, const Epi& E) {
;     ...
;         const bool has_next = S.next(ui + 1, nxt);
;         const char* nA = has_next ? (const char*)(g.A + (size_t)nxt.pm * BM * g.lda + (size_t)nxt.z * g.za) : cA;
;         const char* nB = has_next ? (const char*)(g.Bt + (size_t)nxt.pn * BM * g.ldb + (size_t)nxt.z * g.zb) : cB;
;         for (int t = 0; t < nt; t += 2) {
;             const bool last = (t == nt - 2);
;             const char* a1 = cA + (size_t)(t + 1) * kstep;
;             const char* a2 = last ? nA : cA + (size_t)(t + 2) * kstep; const char* b2 = last ? nB : cB + (size_t)(t + 2) * kstep;
;             const char* a3 = a2 + kstep; const char* b3 = b2 + kstep;
;             PG8_LDB(B0, 0, 0); PG8_LDB(B1, 0, 1); PG8_SCHED; PG8_LDA(At, 0, 0); PG8_STAGE(PG8_SA(1, 1), a1 + hstepA, voffA);
;             PG8_WAIT_V(8); PG8_WAIT_L(0); PG8_BAR; PG8_MMA(0, 0, At, B0); PG8_MMA(0, 1, At, B1); PG8_BAR; PG8_SCHED;
;             PG8_LDA(At, 0, 1); PG8_STAGE(PG8_SB(0, 0), b2, voffB); PG8_STAGE(PG8_SB(0, 1), b2 + hstepB, voffB); PG8_STAGE(PG8_SA(0, 0), a2, voffA);
;             PG8_WAIT_V(8); PG8_WAIT_L(0); PG8_BAR; PG8_MMA(1, 0, At, B0); PG8_MMA(1, 1, At, B1); PG8_BAR; PG8_SCHED;
.LBB0_413:
	s_add_u32 s4, s48, 0xfffc0080
	s_addc_u32 s5, s49, -1
	s_add_i32 s36, 0, 0x10000
	s_cmp_eq_u32 s66, 12
	s_cselect_b32 s65, s30, s5
	s_cselect_b32 s64, s31, s4
	v_add_u32_e32 v138, s36, v141
	s_cselect_b32 s51, s34, s43
	s_cselect_b32 s50, s35, s41
	s_add_i32 s4, 0, 0x14000
	ds_read_b128 v[144:147], v138
	ds_read_b128 v[148:151], v138 offset:1024
	ds_read_b128 v[152:155], v138 offset:2048
	ds_read_b128 v[156:159], v138 offset:3072
	v_add_u32_e32 v138, s4, v141
	ds_read_b128 v[172:175], v138
	ds_read_b128 v[176:179], v138 offset:1024
	ds_read_b128 v[180:183], v138 offset:2048
	ds_read_b128 v[184:187], v138 offset:3072
	s_add_i32 m0, s21, 0xc000
	ds_read_b128 v[188:191], v143
	ds_read_b128 v[192:195], v143 offset:1024
	ds_read_b128 v[214:217], v143 offset:2048
	ds_read_b128 v[218:221], v143 offset:3072
	ds_read_b128 v[222:225], v143 offset:4096
	ds_read_b128 v[226:229], v143 offset:5120
	ds_read_b128 v[230:233], v143 offset:6144
	ds_read_b128 v[234:237], v143 offset:7168
	global_load_lds_dwordx4 v134, s[48:49]
	s_add_i32 m0, s21, 0xe000
	s_nop 0
	global_load_lds_dwordx4 v136, s[48:49]
	s_waitcnt vmcnt(8)
	s_waitcnt lgkmcnt(0)
	s_barrier
	s_setprio 1
	s_waitcnt lgkmcnt(0)
	v_mfma_f32_16x16x32_bf16 v[124:127], v[144:147], v[188:191], v[124:127]
	v_mfma_f32_16x16x32_bf16 v[120:123], v[152:155], v[188:191], v[120:123]
	v_mfma_f32_16x16x32_bf16 v[116:119], v[144:147], v[214:217], v[116:119]
	v_mfma_f32_16x16x32_bf16 v[108:111], v[152:155], v[214:217], v[108:111]
	v_mfma_f32_16x16x32_bf16 v[100:103], v[144:147], v[222:225], v[100:103]
	v_mfma_f32_16x16x32_bf16 v[92:95], v[152:155], v[222:225], v[92:95]
	v_mfma_f32_16x16x32_bf16 v[84:87], v[144:147], v[230:233], v[84:87]
	v_mfma_f32_16x16x32_bf16 v[76:79], v[152:155], v[230:233], v[76:79]
	v_mfma_f32_16x16x32_bf16 v[124:127], v[148:151], v[192:195], v[124:127]
	v_mfma_f32_16x16x32_bf16 v[120:123], v[156:159], v[192:195], v[120:123]
	v_mfma_f32_16x16x32_bf16 v[116:119], v[148:151], v[218:221], v[116:119]
	v_mfma_f32_16x16x32_bf16 v[108:111], v[156:159], v[218:221], v[108:111]
	v_mfma_f32_16x16x32_bf16 v[100:103], v[148:151], v[226:229], v[100:103]
	v_mfma_f32_16x16x32_bf16 v[92:95], v[156:159], v[226:229], v[92:95]
	v_mfma_f32_16x16x32_bf16 v[84:87], v[148:151], v[234:237], v[84:87]
	v_mfma_f32_16x16x32_bf16 v[76:79], v[156:159], v[234:237], v[76:79]
	v_mfma_f32_16x16x32_bf16 v[112:115], v[172:175], v[188:191], v[112:115]
	v_mfma_f32_16x16x32_bf16 v[104:107], v[180:183], v[188:191], v[104:107]
	v_mfma_f32_16x16x32_bf16 v[96:99], v[172:175], v[214:217], v[96:99]
	v_mfma_f32_16x16x32_bf16 v[88:91], v[180:183], v[214:217], v[88:91]
	v_mfma_f32_16x16x32_bf16 v[80:83], v[172:175], v[222:225], v[80:83]
	v_mfma_f32_16x16x32_bf16 v[72:75], v[180:183], v[222:225], v[72:75]
	v_mfma_f32_16x16x32_bf16 v[68:71], v[172:175], v[230:233], v[68:71]
	v_mfma_f32_16x16x32_bf16 v[64:67], v[180:183], v[230:233], v[64:67]
	v_mfma_f32_16x16x32_bf16 v[112:115], v[176:179], v[192:195], v[112:115]
	v_mfma_f32_16x16x32_bf16 v[104:107], v[184:187], v[192:195], v[104:107]
	v_mfma_f32_16x16x32_bf16 v[96:99], v[176:179], v[218:221], v[96:99]
	v_mfma_f32_16x16x32_bf16 v[88:91], v[184:187], v[218:221], v[88:91]
	v_mfma_f32_16x16x32_bf16 v[80:83], v[176:179], v[226:229], v[80:83]
	v_mfma_f32_16x16x32_bf16 v[72:75], v[184:187], v[226:229], v[72:75]
	v_mfma_f32_16x16x32_bf16 v[68:71], v[176:179], v[234:237], v[68:71]
	v_mfma_f32_16x16x32_bf16 v[64:67], v[184:187], v[234:237], v[64:67]
	s_setprio 0
	s_barrier
	s_add_i32 s5, s36, s1
	s_mov_b32 m0, s5
	ds_read_b128 v[188:191], v143 offset:16384
	ds_read_b128 v[192:195], v143 offset:17408
	ds_read_b128 v[214:217], v143 offset:18432
	ds_read_b128 v[218:221], v143 offset:19456
	ds_read_b128 v[222:225], v143 offset:20480
	ds_read_b128 v[226:229], v143 offset:21504
	ds_read_b128 v[230:233], v143 offset:22528
	ds_read_b128 v[234:237], v143 offset:23552
	global_load_lds_dwordx4 v160, s[50:51]
	s_add_i32 m0, s5, 0x2000
	s_add_u32 s36, s50, 0x40000
	s_addc_u32 s37, s51, 0
	s_add_i32 s4, s4, s1
	global_load_lds_dwordx4 v128, s[50:51]
	s_mov_b32 m0, s4
	s_nop 0
	global_load_lds_dwordx4 v160, s[36:37]
	s_add_i32 m0, s4, 0x2000
	s_nop 0
	global_load_lds_dwordx4 v128, s[36:37]
	s_mov_b32 m0, s21
	s_nop 0
	global_load_lds_dwordx4 v132, s[64:65]
	s_mov_b32 m0, s22
	s_nop 0
	global_load_lds_dwordx4 v130, s[64:65]
	s_waitcnt vmcnt(8)
	s_waitcnt lgkmcnt(0)
	s_barrier
	s_setprio 1
	s_waitcnt lgkmcnt(0)
	v_mfma_f32_16x16x32_bf16 v[60:63], v[144:147], v[188:191], v[60:63]
	v_mfma_f32_16x16x32_bf16 v[56:59], v[152:155], v[188:191], v[56:59]
	v_mfma_f32_16x16x32_bf16 v[52:55], v[144:147], v[214:217], v[52:55]
	v_mfma_f32_16x16x32_bf16 v[44:47], v[152:155], v[214:217], v[44:47]
	v_mfma_f32_16x16x32_bf16 v[36:39], v[144:147], v[222:225], v[36:39]
	v_mfma_f32_16x16x32_bf16 v[28:31], v[152:155], v[222:225], v[28:31]
	v_mfma_f32_16x16x32_bf16 v[20:23], v[144:147], v[230:233], v[20:23]
	v_mfma_f32_16x16x32_bf16 v[12:15], v[152:155], v[230:233], v[12:15]
	v_mfma_f32_16x16x32_bf16 v[60:63], v[148:151], v[192:195], v[60:63]
	v_mfma_f32_16x16x32_bf16 v[56:59], v[156:159], v[192:195], v[56:59]
	v_mfma_f32_16x16x32_bf16 v[52:55], v[148:151], v[218:221], v[52:55]
	v_mfma_f32_16x16x32_bf16 v[44:47], v[156:159], v[218:221], v[44:47]
	v_mfma_f32_16x16x32_bf16 v[36:39], v[148:151], v[226:229], v[36:39]
	v_mfma_f32_16x16x32_bf16 v[28:31], v[156:159], v[226:229], v[28:31]
	v_mfma_f32_16x16x32_bf16 v[20:23], v[148:151], v[234:237], v[20:23]
	v_mfma_f32_16x16x32_bf16 v[12:15], v[156:159], v[234:237], v[12:15]
	v_mfma_f32_16x16x32_bf16 v[48:51], v[172:175], v[188:191], v[48:51]
	v_mfma_f32_16x16x32_bf16 v[40:43], v[180:183], v[188:191], v[40:43]
	v_mfma_f32_16x16x32_bf16 v[32:35], v[172:175], v[214:217], v[32:35]
	v_mfma_f32_16x16x32_bf16 v[24:27], v[180:183], v[214:217], v[24:27]
	v_mfma_f32_16x16x32_bf16 v[16:19], v[172:175], v[222:225], v[16:19]
	v_mfma_f32_16x16x32_bf16 v[8:11], v[180:183], v[222:225], v[8:11]
	v_mfma_f32_16x16x32_bf16 v[4:7], v[172:175], v[230:233], v[4:7]
	v_mfma_f32_16x16x32_bf16 v[0:3], v[180:183], v[230:233], v[0:3]
	v_mfma_f32_16x16x32_bf16 v[48:51], v[176:179], v[192:195], v[48:51]
	v_mfma_f32_16x16x32_bf16 v[40:43], v[184:187], v[192:195], v[40:43]
	v_mfma_f32_16x16x32_bf16 v[32:35], v[176:179], v[218:221], v[32:35]
	v_mfma_f32_16x16x32_bf16 v[24:27], v[184:187], v[218:221], v[24:27]
	v_mfma_f32_16x16x32_bf16 v[16:19], v[176:179], v[226:229], v[16:19]
	v_mfma_f32_16x16x32_bf16 v[8:11], v[184:187], v[226:229], v[8:11]
	v_mfma_f32_16x16x32_bf16 v[4:7], v[176:179], v[234:237], v[4:7]
	v_mfma_f32_16x16x32_bf16 v[0:3], v[184:187], v[234:237], v[0:3]
	s_setprio 0
	s_barrier
; #define PG8_STAGE(bufoff, gbase, voff) do { _Pragma("unroll") for (int _i = 0; _i < 2; ++_i) \
;         __builtin_amdgcn_global_load_lds((const unsigned*)((const char*)(gbase) + (voff)[_i]), (LAS unsigned*)(lds + (bufoff) + ldsw + _i * 8192), 16, 0, 0); } while (0)
; #define PG8_LDA(dst, b, h) do { _Pragma("unroll") for (int m = 0; m < 4; ++m) _Pragma("unroll") for (int k = 0; k < 2; ++k) dst[m][k] = *(const LAS bf16x8*)(lds + PG8_SA(b, h) + aoff + m * 2048 + k * 1024); } while (0)
; #define PG8_LDB(dst, b, h) do { _Pragma("unroll") for (int n = 0; n < 2; ++n) _Pragma("unroll") for (int k = 0; k < 2; ++k) dst[n][k] = *(const LAS bf16x8*)(lds + PG8_SB(b, h) + boff + n * 2048 + k * 1024); } while (0)
; #define PG8_WAIT_V(n) asm volatile("s_waitcnt vmcnt(" #n ")" ::: "memory")
; #define PG8_WAIT_L(n) asm volatile("s_waitcnt lgkmcnt(" #n ")" ::: "memory")
; #define PG8_BAR __builtin_amdgcn_s_barrier()
; #define PG8_SCHED __builtin_amdgcn_sched_barrier(0)
; template <class Epi>
; __device__ __forceinline__ void gemm_phase(LAS unsigned char* lds, const Gemm g, const Order& S, const Epi& E) {
;     ...
;             PG8_LDB(B0, 1, 0); PG8_LDB(B1, 1, 1); PG8_SCHED; PG8_LDA(At, 1, 0); PG8_STAGE(PG8_SA(0, 1), a2 + hstepA, voffA);
;             PG8_WAIT_V(8); PG8_WAIT_L(0); PG8_BAR; PG8_MMA(0, 0, At, B0); PG8_MMA(0, 1, At, B1); PG8_BAR; PG8_SCHED;
;             PG8_LDA(At, 1, 1); PG8_STAGE(PG8_SB(1, 0), b3, voffB); PG8_STAGE(PG8_SB(1, 1), b3 + hstepB, voffB); PG8_STAGE(PG8_SA(1, 0), a3, voffA);
;             PG8_WAIT_V(8); PG8_WAIT_L(0); PG8_BAR; PG8_MMA(1, 0, At, B0); PG8_MMA(1, 1, At, B1); PG8_BAR; PG8_SCHED;
;         }
;         if constexpr (ALIGN_EPI) { if (wr == 0) PG8_BAR; }
;         if constexpr (!Epi::AFTER_DRAIN) E(acc, cur, wr, wc, fr, fq);
;         if (!has_next) break;
	s_add_i32 s4, 0, 0x18000
	s_add_i32 s5, 0, 0x1c000
	v_add_u32_e32 v156, s4, v141
	v_add_u32_e32 v171, s5, v141
	ds_read_b128 v[144:147], v156
	ds_read_b128 v[148:151], v156 offset:1024
	ds_read_b128 v[152:155], v156 offset:2048
	ds_read_b128 v[156:159], v156 offset:3072
	ds_read_b128 v[172:175], v171
	ds_read_b128 v[176:179], v171 offset:1024
	ds_read_b128 v[180:183], v171 offset:2048
	ds_read_b128 v[184:187], v171 offset:3072
	s_add_u32 s36, s64, 0x40000
	s_addc_u32 s37, s65, 0
	s_mov_b32 m0, s23
	ds_read_b128 v[188:191], v143 offset:32768
	ds_read_b128 v[192:195], v143 offset:33792
	ds_read_b128 v[214:217], v143 offset:34816
	ds_read_b128 v[218:221], v143 offset:35840
	ds_read_b128 v[222:225], v143 offset:36864
	ds_read_b128 v[226:229], v143 offset:37888
	ds_read_b128 v[230:233], v143 offset:38912
	ds_read_b128 v[234:237], v143 offset:39936
	global_load_lds_dwordx4 v132, s[36:37]
	s_mov_b32 m0, s24
	s_nop 0
	global_load_lds_dwordx4 v130, s[36:37]
	s_waitcnt vmcnt(8)
	s_waitcnt lgkmcnt(0)
	s_barrier
	s_setprio 1
	s_waitcnt lgkmcnt(0)
	v_mfma_f32_16x16x32_bf16 v[124:127], v[144:147], v[188:191], v[124:127]
	v_mfma_f32_16x16x32_bf16 v[120:123], v[152:155], v[188:191], v[120:123]
	v_mfma_f32_16x16x32_bf16 v[116:119], v[144:147], v[214:217], v[116:119]
	v_mfma_f32_16x16x32_bf16 v[108:111], v[152:155], v[214:217], v[108:111]
	v_mfma_f32_16x16x32_bf16 v[100:103], v[144:147], v[222:225], v[100:103]
	v_mfma_f32_16x16x32_bf16 v[92:95], v[152:155], v[222:225], v[92:95]
	v_mfma_f32_16x16x32_bf16 v[84:87], v[144:147], v[230:233], v[84:87]
	v_mfma_f32_16x16x32_bf16 v[76:79], v[152:155], v[230:233], v[76:79]
	v_mfma_f32_16x16x32_bf16 v[124:127], v[148:151], v[192:195], v[124:127]
	v_mfma_f32_16x16x32_bf16 v[120:123], v[156:159], v[192:195], v[120:123]
	v_mfma_f32_16x16x32_bf16 v[116:119], v[148:151], v[218:221], v[116:119]
	v_mfma_f32_16x16x32_bf16 v[108:111], v[156:159], v[218:221], v[108:111]
	v_mfma_f32_16x16x32_bf16 v[100:103], v[148:151], v[226:229], v[100:103]
	v_mfma_f32_16x16x32_bf16 v[92:95], v[156:159], v[226:229], v[92:95]
	v_mfma_f32_16x16x32_bf16 v[84:87], v[148:151], v[234:237], v[84:87]
	v_mfma_f32_16x16x32_bf16 v[76:79], v[156:159], v[234:237], v[76:79]
	v_mfma_f32_16x16x32_bf16 v[112:115], v[172:175], v[188:191], v[112:115]
	v_mfma_f32_16x16x32_bf16 v[104:107], v[180:183], v[188:191], v[104:107]
	v_mfma_f32_16x16x32_bf16 v[96:99], v[172:175], v[214:217], v[96:99]
	v_mfma_f32_16x16x32_bf16 v[88:91], v[180:183], v[214:217], v[88:91]
	v_mfma_f32_16x16x32_bf16 v[80:83], v[172:175], v[222:225], v[80:83]
	v_mfma_f32_16x16x32_bf16 v[72:75], v[180:183], v[222:225], v[72:75]
	v_mfma_f32_16x16x32_bf16 v[68:71], v[172:175], v[230:233], v[68:71]
	v_mfma_f32_16x16x32_bf16 v[64:67], v[180:183], v[230:233], v[64:67]
	v_mfma_f32_16x16x32_bf16 v[112:115], v[176:179], v[192:195], v[112:115]
	v_mfma_f32_16x16x32_bf16 v[104:107], v[184:187], v[192:195], v[104:107]
	v_mfma_f32_16x16x32_bf16 v[96:99], v[176:179], v[218:221], v[96:99]
	v_mfma_f32_16x16x32_bf16 v[88:91], v[184:187], v[218:221], v[88:91]
	v_mfma_f32_16x16x32_bf16 v[80:83], v[176:179], v[226:229], v[80:83]
	v_mfma_f32_16x16x32_bf16 v[72:75], v[184:187], v[226:229], v[72:75]
	v_mfma_f32_16x16x32_bf16 v[68:71], v[176:179], v[234:237], v[68:71]
	v_mfma_f32_16x16x32_bf16 v[64:67], v[184:187], v[234:237], v[64:67]
	s_setprio 0
	s_barrier
	s_add_i32 s4, s4, s1
	s_add_u32 s100, s50, 0x80
	s_addc_u32 s101, s51, 0
	s_mov_b32 m0, s4
	ds_read_b128 v[188:191], v143 offset:49152
	ds_read_b128 v[192:195], v143 offset:50176
	ds_read_b128 v[214:217], v143 offset:51200
	ds_read_b128 v[218:221], v143 offset:52224
	ds_read_b128 v[222:225], v143 offset:53248
	ds_read_b128 v[226:229], v143 offset:54272
	ds_read_b128 v[230:233], v143 offset:55296
	ds_read_b128 v[234:237], v143 offset:56320
	global_load_lds_dwordx4 v160, s[100:101]
	s_add_i32 m0, s4, 0x2000
	s_add_u32 s36, s50, 0x40080
	s_addc_u32 s37, s51, 0
	s_add_i32 s4, s5, s1
	global_load_lds_dwordx4 v128, s[100:101]
	s_mov_b32 m0, s4
	s_nop 0
	global_load_lds_dwordx4 v160, s[36:37]
	s_add_i32 m0, s4, 0x2000
	s_nop 0
	global_load_lds_dwordx4 v128, s[36:37]
	s_add_u32 s100, s64, 0x80
	s_addc_u32 s101, s65, 0
	s_mov_b32 m0, s25
	s_nop 0
	global_load_lds_dwordx4 v132, s[100:101]
	s_mov_b32 m0, s26
	s_nop 0
	global_load_lds_dwordx4 v130, s[100:101]
	s_waitcnt vmcnt(8)
	s_waitcnt lgkmcnt(0)
	s_barrier
	s_setprio 1
	s_waitcnt lgkmcnt(0)
	v_mfma_f32_16x16x32_bf16 v[60:63], v[144:147], v[188:191], v[60:63]
	v_mfma_f32_16x16x32_bf16 v[56:59], v[152:155], v[188:191], v[56:59]
	v_mfma_f32_16x16x32_bf16 v[52:55], v[144:147], v[214:217], v[52:55]
	v_mfma_f32_16x16x32_bf16 v[44:47], v[152:155], v[214:217], v[44:47]
	v_mfma_f32_16x16x32_bf16 v[36:39], v[144:147], v[222:225], v[36:39]
	v_mfma_f32_16x16x32_bf16 v[28:31], v[152:155], v[222:225], v[28:31]
	v_mfma_f32_16x16x32_bf16 v[20:23], v[144:147], v[230:233], v[20:23]
	v_mfma_f32_16x16x32_bf16 v[12:15], v[152:155], v[230:233], v[12:15]
	v_mfma_f32_16x16x32_bf16 v[60:63], v[148:151], v[192:195], v[60:63]
	v_mfma_f32_16x16x32_bf16 v[56:59], v[156:159], v[192:195], v[56:59]
	v_mfma_f32_16x16x32_bf16 v[52:55], v[148:151], v[218:221], v[52:55]
	v_mfma_f32_16x16x32_bf16 v[44:47], v[156:159], v[218:221], v[44:47]
	v_mfma_f32_16x16x32_bf16 v[36:39], v[148:151], v[226:229], v[36:39]
	v_mfma_f32_16x16x32_bf16 v[28:31], v[156:159], v[226:229], v[28:31]
	v_mfma_f32_16x16x32_bf16 v[20:23], v[148:151], v[234:237], v[20:23]
	v_mfma_f32_16x16x32_bf16 v[12:15], v[156:159], v[234:237], v[12:15]
	v_mfma_f32_16x16x32_bf16 v[48:51], v[172:175], v[188:191], v[48:51]
	v_mfma_f32_16x16x32_bf16 v[40:43], v[180:183], v[188:191], v[40:43]
	v_mfma_f32_16x16x32_bf16 v[32:35], v[172:175], v[214:217], v[32:35]
	v_mfma_f32_16x16x32_bf16 v[24:27], v[180:183], v[214:217], v[24:27]
	v_mfma_f32_16x16x32_bf16 v[16:19], v[172:175], v[222:225], v[16:19]
	v_mfma_f32_16x16x32_bf16 v[8:11], v[180:183], v[222:225], v[8:11]
	v_mfma_f32_16x16x32_bf16 v[4:7], v[172:175], v[230:233], v[4:7]
	v_mfma_f32_16x16x32_bf16 v[0:3], v[180:183], v[230:233], v[0:3]
	v_mfma_f32_16x16x32_bf16 v[48:51], v[176:179], v[192:195], v[48:51]
	v_mfma_f32_16x16x32_bf16 v[40:43], v[184:187], v[192:195], v[40:43]
	v_mfma_f32_16x16x32_bf16 v[32:35], v[176:179], v[218:221], v[32:35]
	v_mfma_f32_16x16x32_bf16 v[24:27], v[184:187], v[218:221], v[24:27]
	v_mfma_f32_16x16x32_bf16 v[16:19], v[176:179], v[226:229], v[16:19]
	v_mfma_f32_16x16x32_bf16 v[8:11], v[184:187], v[226:229], v[8:11]
	v_mfma_f32_16x16x32_bf16 v[4:7], v[176:179], v[234:237], v[4:7]
	v_mfma_f32_16x16x32_bf16 v[0:3], v[184:187], v[234:237], v[0:3]
	s_setprio 0
	s_barrier
	s_add_i32 s66, s66, 2
	s_add_u32 s48, s48, 0x100
	s_addc_u32 s49, s49, 0
	s_add_u32 s41, s41, 0x100
	s_addc_u32 s43, s43, 0
	s_cmp_gt_u32 s66, 13
	s_cbranch_scc0 .LBB0_413
	s_and_b64 vcc, exec, s[12:13]
	s_cbranch_vccz .LBB0_416
	s_barrier
